# PROJ and RESID K-loops: B-fragment LDS read addresses use one hoisted base + ds offset immediates (16 VALU fewer per iteration per wave)
# baseline (speedup 1.0000x reference)
; #define PG8_WAIT_V(n) asm volatile("s_waitcnt vmcnt(" #n ")" ::: "memory")
; template <int EPI, bool ALIGN_EPI = true, bool SP2 = true>
; DI void gemm8_phase(const GemmArgs& g, char* lds_) {
;     ...
;   f32x4 acc[2][2][4][2];
; #pragma unroll
;   for (int a = 0; a < 2; ++a)
; #pragma unroll
;     for (int b = 0; b < 2; ++b)
; #pragma unroll
;       for (int m = 0; m < 4; ++m)
; #pragma unroll
;         for (int n = 0; n < 2; ++n) acc[a][b][m][n] = f32x4{0.f, 0.f, 0.f, 0.f};
;   bf16x8 At[4][2], B0[2][2], B1[2][2];
;   const char* cA = (const char*)g.A0 + (size_t)cpm * tstep;
;   const char* cB = (const char*)g.Bt0 + (size_t)cpn * tstep;
;   PG8_WAIT_V(0);
;   __syncthreads();
;   if constexpr (SP2) {
;     PG8_STAGE(PG8_SB(0, 0), cB); PG8_STAGE(PG8_SB(0, 1), cB + hstep); PG8_STAGE(PG8_SA(0, 0), cA); PG8_STAGE(PG8_SA(0, 1), cA + hstep);
;     if (wr == 1) PG8_BAR;
;     PG8_WAIT_V(2); PG8_BAR;
;     PG8_STAGE(PG8_SB(1, 0), cB + kstep); PG8_STAGE(PG8_SA(1, 0), cA + kstep); PG8_STAGE(PG8_SB(1, 1), cB + hstep + kstep);
;     PG8_WAIT_V(6); PG8_BAR;
;   } else {
;     PG8_STAGE(PG8_SB(0, 0), cB); PG8_STAGE(PG8_SA(0, 0), cA); PG8_STAGE(PG8_SB(0, 1), cB + hstep); PG8_STAGE(PG8_SA(0, 1), cA + hstep);
;     if (wr == 1) PG8_BAR;
;     PG8_WAIT_V(4); PG8_BAR;
;     PG8_STAGE(PG8_SB(1, 0), cB + kstep); PG8_STAGE(PG8_SA(1, 0), cA + kstep); PG8_STAGE(PG8_SB(1, 1), cB + hstep + kstep);
;     PG8_WAIT_V(6); PG8_BAR;
;   }
;   for (;;) {
;     const int nid = (int)blockIdx.x + (ui + 1) * G;
;     const bool has_next = nid < total;
;     if (has_next) tile_map(nid, g.NTm, g.NTn, npm, npn, g.gm);
;     const char* nA = has_next ? (const char*)g.A0 + (size_t)npm * tstep : cA;
;     const char* nB = has_next ? (const char*)g.Bt0 + (size_t)npn * tstep : cB;
; #pragma unroll 1
;     for (int t = 0; t < nt; t += 2) {
;       const bool last = (t == nt - 2);
;       const char* a1 = cA + (size_t)(t + 1) * kstep;
;       const char* a2 = last ? nA : cA + (size_t)(t + 2) * kstep;
;       const char* b2 = last ? nB : cB + (size_t)(t + 2) * kstep;
;       const char* a3 = a2 + kstep; const char* b3 = b2 + kstep;
;       if constexpr (SP2) {
;         const bool relax = EPI_VM > 0 && t == 0 && ui > 0;
;         PG8_LDB(B0, 0, 0); PG8_LDB(B1, 0, 1); PG8_SCHED; PG8_LDA(At, 0, 0); PG8_STAGE(PG8_SA(1, 1), a1 + hstep);
;         if (relax) PG8_WAIT_V(24); else PG8_WAIT_V(8);
.LBB0_380:
	s_ashr_i32 s45, s44, 31
	s_lshl_b64 s[24:25], s[44:45], 19
	s_add_u32 s84, s7, s24
	s_addc_u32 s85, s8, s25
	s_and_b64 s[24:25], s[62:63], exec
	s_cselect_b32 s45, s85, s41
	s_cselect_b32 s47, s84, s40
	s_add_u32 s50, s40, 0x100
	v_mov_b32_e32 v2, 0
	s_addc_u32 s51, s41, 0
	s_mov_b32 vcc_lo, -2
	v_mov_b32_e32 v3, v2
	v_mov_b32_e32 v4, v2
	v_mov_b32_e32 v5, v2
	v_mov_b32_e32 v6, v2
	v_mov_b32_e32 v7, v2
	v_mov_b32_e32 v8, v2
	v_mov_b32_e32 v9, v2
	v_mov_b32_e32 v10, v2
	v_mov_b32_e32 v11, v2
	v_mov_b32_e32 v12, v2
	v_mov_b32_e32 v13, v2
	v_mov_b32_e32 v14, v2
	v_mov_b32_e32 v15, v2
	v_mov_b32_e32 v16, v2
	v_mov_b32_e32 v17, v2
	v_mov_b32_e32 v18, v2
	v_mov_b32_e32 v19, v2
	v_mov_b32_e32 v20, v2
	v_mov_b32_e32 v21, v2
	v_mov_b32_e32 v22, v2
	v_mov_b32_e32 v23, v2
	v_mov_b32_e32 v24, v2
	v_mov_b32_e32 v25, v2
	v_mov_b32_e32 v26, v2
	v_mov_b32_e32 v27, v2
	v_mov_b32_e32 v28, v2
	v_mov_b32_e32 v29, v2
	v_mov_b32_e32 v30, v2
	v_mov_b32_e32 v31, v2
	v_mov_b32_e32 v32, v2
	v_mov_b32_e32 v33, v2
	v_mov_b32_e32 v34, v2
	v_mov_b32_e32 v35, v2
	v_mov_b32_e32 v36, v2
	v_mov_b32_e32 v37, v2
	v_mov_b32_e32 v38, v2
	v_mov_b32_e32 v39, v2
	v_mov_b32_e32 v40, v2
	v_mov_b32_e32 v41, v2
	v_mov_b32_e32 v42, v2
	v_mov_b32_e32 v43, v2
	v_mov_b32_e32 v44, v2
	v_mov_b32_e32 v45, v2
	v_mov_b32_e32 v46, v2
	v_mov_b32_e32 v47, v2
	v_mov_b32_e32 v48, v2
	v_mov_b32_e32 v49, v2
	v_mov_b32_e32 v50, v2
	v_mov_b32_e32 v51, v2
	v_mov_b32_e32 v52, v2
	v_mov_b32_e32 v53, v2
	v_mov_b32_e32 v54, v2
	v_mov_b32_e32 v55, v2
	v_mov_b32_e32 v56, v2
	v_mov_b32_e32 v57, v2
	v_mov_b32_e32 v58, v2
	v_mov_b32_e32 v59, v2
	v_mov_b32_e32 v60, v2
	v_mov_b32_e32 v61, v2
	v_mov_b32_e32 v62, v2
	v_mov_b32_e32 v63, v2
	v_mov_b32_e32 v64, v2
	v_mov_b32_e32 v65, v2
	v_mov_b32_e32 v66, v2
	v_mov_b32_e32 v67, v2
	v_mov_b32_e32 v68, v2
	v_mov_b32_e32 v69, v2
	v_mov_b32_e32 v70, v2
	v_mov_b32_e32 v71, v2
	v_mov_b32_e32 v72, v2
	v_mov_b32_e32 v73, v2
	v_mov_b32_e32 v74, v2
	v_mov_b32_e32 v75, v2
	v_mov_b32_e32 v76, v2
	v_mov_b32_e32 v77, v2
	v_mov_b32_e32 v78, v2
	v_mov_b32_e32 v79, v2
	v_mov_b32_e32 v80, v2
	v_mov_b32_e32 v81, v2
	v_mov_b32_e32 v82, v2
	v_mov_b32_e32 v83, v2
	v_mov_b32_e32 v84, v2
	v_mov_b32_e32 v85, v2
	v_mov_b32_e32 v86, v2
	v_mov_b32_e32 v87, v2
	v_mov_b32_e32 v88, v2
	v_mov_b32_e32 v89, v2
	v_mov_b32_e32 v90, v2
	v_mov_b32_e32 v91, v2
	v_mov_b32_e32 v92, v2
	v_mov_b32_e32 v93, v2
	v_mov_b32_e32 v94, v2
	v_mov_b32_e32 v95, v2
	v_mov_b32_e32 v96, v2
	v_mov_b32_e32 v97, v2
	v_mov_b32_e32 v98, v2
	v_mov_b32_e32 v99, v2
	v_mov_b32_e32 v100, v2
	v_mov_b32_e32 v101, v2
	v_mov_b32_e32 v102, v2
	v_mov_b32_e32 v103, v2
	v_mov_b32_e32 v104, v2
	v_mov_b32_e32 v105, v2
	v_mov_b32_e32 v106, v2
	v_mov_b32_e32 v107, v2
	v_mov_b32_e32 v108, v2
	v_mov_b32_e32 v109, v2
	v_mov_b32_e32 v110, v2
	v_mov_b32_e32 v111, v2
	v_mov_b32_e32 v112, v2
	v_mov_b32_e32 v113, v2
	v_mov_b32_e32 v114, v2
	v_mov_b32_e32 v115, v2
	v_mov_b32_e32 v116, v2
	v_mov_b32_e32 v117, v2
	v_mov_b32_e32 v118, v2
	v_mov_b32_e32 v119, v2
	v_mov_b32_e32 v120, v2
	v_mov_b32_e32 v121, v2
	v_mov_b32_e32 v122, v2
	v_mov_b32_e32 v123, v2
	v_mov_b32_e32 v124, v2
	v_mov_b32_e32 v125, v2
	v_mov_b32_e32 v126, v2
	v_mov_b32_e32 v127, v2
	v_mov_b32_e32 v128, v2
	v_mov_b32_e32 v129, v2
	v_add_u32_e32 v164, 0x80, v130
	v_add_u32_e32 v165, 0x80, v132
	v_add_u32_e32 v172, 0x10000, v149
.LBB0_381:
	ds_read_b128 v[138:141], v172
	ds_read_b128 v[142:145], v172 offset:1024
	ds_read_b128 v[154:157], v172 offset:2048
	ds_read_b128 v[158:161], v172 offset:3072
	ds_read_b128 v[168:171], v172 offset:16384
	ds_read_b128 v[192:195], v172 offset:17408
	ds_read_b128 v[196:199], v172 offset:18432
	ds_read_b128 v[200:203], v172 offset:19456
	s_add_u32 s40, s34, 0x100
	s_addc_u32 s41, s35, 0
	s_cmp_eq_u32 vcc_lo, 12
	s_cselect_b32 s91, s49, s41
	s_cselect_b32 s90, s48, s40
	s_cselect_b32 s87, s45, s51
	s_cselect_b32 s86, s47, s50
	s_add_i32 m0, s9, 0xc000
	ds_read_b128 v[204:207], v150
	ds_read_b128 v[208:211], v150 offset:1024
	ds_read_b128 v[212:215], v150 offset:2048
	ds_read_b128 v[216:219], v150 offset:3072
	ds_read_b128 v[220:223], v150 offset:4096
	ds_read_b128 v[224:227], v150 offset:5120
	ds_read_b128 v[228:231], v150 offset:6144
	ds_read_b128 v[232:235], v150 offset:7168
	global_load_lds_dwordx4 v134, s[34:35]
	s_add_i32 m0, s9, 0xe000
	s_nop 0
	global_load_lds_dwordx4 v136, s[34:35]
	s_waitcnt vmcnt(8)
	s_waitcnt lgkmcnt(0)
	s_barrier
	s_setprio 1
	s_waitcnt lgkmcnt(0)
	v_mfma_f32_16x16x32_bf16 v[126:129], v[138:141], v[204:207], v[126:129]
	v_mfma_f32_16x16x32_bf16 v[122:125], v[154:157], v[204:207], v[122:125]
	v_mfma_f32_16x16x32_bf16 v[118:121], v[138:141], v[212:215], v[118:121]
	v_mfma_f32_16x16x32_bf16 v[114:117], v[154:157], v[212:215], v[114:117]
	v_mfma_f32_16x16x32_bf16 v[110:113], v[138:141], v[220:223], v[110:113]
	v_mfma_f32_16x16x32_bf16 v[106:109], v[154:157], v[220:223], v[106:109]
	v_mfma_f32_16x16x32_bf16 v[102:105], v[138:141], v[228:231], v[102:105]
	v_mfma_f32_16x16x32_bf16 v[98:101], v[154:157], v[228:231], v[98:101]
	v_mfma_f32_16x16x32_bf16 v[126:129], v[142:145], v[208:211], v[126:129]
	v_mfma_f32_16x16x32_bf16 v[122:125], v[158:161], v[208:211], v[122:125]
	v_mfma_f32_16x16x32_bf16 v[118:121], v[142:145], v[216:219], v[118:121]
	v_mfma_f32_16x16x32_bf16 v[114:117], v[158:161], v[216:219], v[114:117]
	v_mfma_f32_16x16x32_bf16 v[110:113], v[142:145], v[224:227], v[110:113]
	v_mfma_f32_16x16x32_bf16 v[106:109], v[158:161], v[224:227], v[106:109]
	v_mfma_f32_16x16x32_bf16 v[102:105], v[142:145], v[232:235], v[102:105]
	v_mfma_f32_16x16x32_bf16 v[98:101], v[158:161], v[232:235], v[98:101]
	s_setprio 0
	s_setprio 1
	v_mfma_f32_16x16x32_bf16 v[94:97], v[168:171], v[204:207], v[94:97]
	v_mfma_f32_16x16x32_bf16 v[90:93], v[196:199], v[204:207], v[90:93]
	v_mfma_f32_16x16x32_bf16 v[86:89], v[168:171], v[212:215], v[86:89]
	v_mfma_f32_16x16x32_bf16 v[82:85], v[196:199], v[212:215], v[82:85]
	v_mfma_f32_16x16x32_bf16 v[78:81], v[168:171], v[220:223], v[78:81]
	v_mfma_f32_16x16x32_bf16 v[74:77], v[196:199], v[220:223], v[74:77]
	v_mfma_f32_16x16x32_bf16 v[70:73], v[168:171], v[228:231], v[70:73]
	v_mfma_f32_16x16x32_bf16 v[66:69], v[196:199], v[228:231], v[66:69]
	v_mfma_f32_16x16x32_bf16 v[94:97], v[192:195], v[208:211], v[94:97]
	v_mfma_f32_16x16x32_bf16 v[90:93], v[200:203], v[208:211], v[90:93]
	v_mfma_f32_16x16x32_bf16 v[86:89], v[192:195], v[216:219], v[86:89]
	v_mfma_f32_16x16x32_bf16 v[82:85], v[200:203], v[216:219], v[82:85]
	v_mfma_f32_16x16x32_bf16 v[78:81], v[192:195], v[224:227], v[78:81]
	v_mfma_f32_16x16x32_bf16 v[74:77], v[200:203], v[224:227], v[74:77]
	v_mfma_f32_16x16x32_bf16 v[70:73], v[192:195], v[232:235], v[70:73]
	v_mfma_f32_16x16x32_bf16 v[66:69], v[200:203], v[232:235], v[66:69]
	s_setprio 0
	s_barrier
; #define PG8_STAGE(bufoff, gbase) do { _Pragma("unroll") for (int _i = 0; _i < 2; ++_i) \
;     __builtin_amdgcn_global_load_lds((const unsigned*)((const char*)(gbase) + voff[_i]), (LAS unsigned*)(lds + (bufoff) + ldsw + _i * 8192), 16, 0, 0); } while (0)
; #define PG8_LDA(dst, b, h) do { _Pragma("unroll") for (int m = 0; m < 4; ++m) _Pragma("unroll") for (int k = 0; k < 2; ++k) dst[m][k] = *(const LAS bf16x8*)(lds + PG8_SA(b, h) + aoff + m * 2048 + k * 1024); } while (0)
; #define PG8_LDB(dst, b, h) do { _Pragma("unroll") for (int n = 0; n < 2; ++n) _Pragma("unroll") for (int k = 0; k < 2; ++k) dst[n][k] = *(const LAS bf16x8*)(lds + PG8_SB(b, h) + boff + n * 2048 + k * 1024); } while (0)
; #define PG8_WAIT_V(n) asm volatile("s_waitcnt vmcnt(" #n ")" ::: "memory")
; #define PG8_WAIT_L(n) asm volatile("s_waitcnt lgkmcnt(" #n ")" ::: "memory")
; #define PG8_BAR __builtin_amdgcn_s_barrier()
; #define PG8_SCHED __builtin_amdgcn_sched_barrier(0)
; template <int EPI, bool ALIGN_EPI = true, bool SP2 = true>
; DI void gemm8_phase(const GemmArgs& g, char* lds_) {
;     ...
;         PG8_WAIT_L(0); PG8_BAR; PG8_MMA(0, 0, At, B0); PG8_MMA(0, 1, At, B1); PG8_BAR; PG8_SCHED;
;         PG8_LDA(At, 0, 1); PG8_STAGE(PG8_SB(0, 0), b2); PG8_STAGE(PG8_SB(0, 1), b2 + hstep); PG8_STAGE(PG8_SA(0, 0), a2);
;         if (relax) PG8_WAIT_V(24); else PG8_WAIT_V(8);
;         PG8_WAIT_L(0); PG8_BAR; PG8_MMA(1, 0, At, B0); PG8_MMA(1, 1, At, B1); PG8_BAR; PG8_SCHED;
;         PG8_LDB(B0, 1, 0); PG8_LDB(B1, 1, 1); PG8_SCHED; PG8_LDA(At, 1, 0); PG8_STAGE(PG8_SA(0, 1), a2 + hstep);
	s_mov_b32 m0, s10
	s_add_u32 s24, s86, 0x40000
	ds_read_b128 v[204:207], v150 offset:16384
	ds_read_b128 v[208:211], v150 offset:17408
	ds_read_b128 v[212:215], v150 offset:18432
	ds_read_b128 v[216:219], v150 offset:19456
	ds_read_b128 v[220:223], v150 offset:20480
	ds_read_b128 v[224:227], v150 offset:21504
	ds_read_b128 v[228:231], v150 offset:22528
	ds_read_b128 v[232:235], v150 offset:23552
	global_load_lds_dwordx4 v130, s[86:87]
	s_mov_b32 m0, s11
	s_addc_u32 s25, s87, 0
	global_load_lds_dwordx4 v132, s[86:87]
	s_mov_b32 m0, s12
	s_nop 0
	global_load_lds_dwordx4 v130, s[24:25]
	s_mov_b32 m0, s13
	s_nop 0
	global_load_lds_dwordx4 v132, s[24:25]
	s_mov_b32 m0, s9
	s_nop 0
	global_load_lds_dwordx4 v130, s[90:91]
	s_mov_b32 m0, s14
	s_nop 0
	global_load_lds_dwordx4 v132, s[90:91]
	s_waitcnt vmcnt(8)
	s_waitcnt lgkmcnt(0)
	s_barrier
	s_setprio 1
	s_waitcnt lgkmcnt(0)
	v_mfma_f32_16x16x32_bf16 v[62:65], v[138:141], v[204:207], v[62:65]
	v_mfma_f32_16x16x32_bf16 v[58:61], v[154:157], v[204:207], v[58:61]
	v_mfma_f32_16x16x32_bf16 v[54:57], v[138:141], v[212:215], v[54:57]
	v_mfma_f32_16x16x32_bf16 v[50:53], v[154:157], v[212:215], v[50:53]
	v_mfma_f32_16x16x32_bf16 v[46:49], v[138:141], v[220:223], v[46:49]
	v_mfma_f32_16x16x32_bf16 v[42:45], v[154:157], v[220:223], v[42:45]
	v_mfma_f32_16x16x32_bf16 v[38:41], v[138:141], v[228:231], v[38:41]
	v_mfma_f32_16x16x32_bf16 v[34:37], v[154:157], v[228:231], v[34:37]
	v_mfma_f32_16x16x32_bf16 v[62:65], v[142:145], v[208:211], v[62:65]
	v_mfma_f32_16x16x32_bf16 v[58:61], v[158:161], v[208:211], v[58:61]
	v_mfma_f32_16x16x32_bf16 v[54:57], v[142:145], v[216:219], v[54:57]
	v_mfma_f32_16x16x32_bf16 v[50:53], v[158:161], v[216:219], v[50:53]
	v_mfma_f32_16x16x32_bf16 v[46:49], v[142:145], v[224:227], v[46:49]
	v_mfma_f32_16x16x32_bf16 v[42:45], v[158:161], v[224:227], v[42:45]
	v_mfma_f32_16x16x32_bf16 v[38:41], v[142:145], v[232:235], v[38:41]
	v_mfma_f32_16x16x32_bf16 v[34:37], v[158:161], v[232:235], v[34:37]
	s_setprio 0
	s_setprio 1
	v_mfma_f32_16x16x32_bf16 v[30:33], v[168:171], v[204:207], v[30:33]
	v_mfma_f32_16x16x32_bf16 v[26:29], v[196:199], v[204:207], v[26:29]
	v_mfma_f32_16x16x32_bf16 v[22:25], v[168:171], v[212:215], v[22:25]
	v_mfma_f32_16x16x32_bf16 v[18:21], v[196:199], v[212:215], v[18:21]
	v_mfma_f32_16x16x32_bf16 v[14:17], v[168:171], v[220:223], v[14:17]
	v_mfma_f32_16x16x32_bf16 v[10:13], v[196:199], v[220:223], v[10:13]
	v_mfma_f32_16x16x32_bf16 v[6:9], v[168:171], v[228:231], v[6:9]
	v_mfma_f32_16x16x32_bf16 v[2:5], v[196:199], v[228:231], v[2:5]
	v_mfma_f32_16x16x32_bf16 v[30:33], v[192:195], v[208:211], v[30:33]
	v_mfma_f32_16x16x32_bf16 v[26:29], v[200:203], v[208:211], v[26:29]
	v_mfma_f32_16x16x32_bf16 v[22:25], v[192:195], v[216:219], v[22:25]
	v_mfma_f32_16x16x32_bf16 v[18:21], v[200:203], v[216:219], v[18:21]
	v_mfma_f32_16x16x32_bf16 v[14:17], v[192:195], v[224:227], v[14:17]
	v_mfma_f32_16x16x32_bf16 v[10:13], v[200:203], v[224:227], v[10:13]
	v_mfma_f32_16x16x32_bf16 v[6:9], v[192:195], v[232:235], v[6:9]
	v_mfma_f32_16x16x32_bf16 v[2:5], v[200:203], v[232:235], v[2:5]
	s_setprio 0
	s_barrier
	ds_read_b128 v[138:141], v172 offset:32768
	ds_read_b128 v[142:145], v172 offset:33792
	ds_read_b128 v[154:157], v172 offset:34816
	ds_read_b128 v[158:161], v172 offset:35840
	ds_read_b128 v[168:171], v172 offset:49152
	ds_read_b128 v[192:195], v172 offset:50176
	ds_read_b128 v[196:199], v172 offset:51200
	ds_read_b128 v[200:203], v172 offset:52224
	s_add_u32 s24, s90, 0x40000
	s_addc_u32 s25, s91, 0
	s_mov_b32 m0, s15
	ds_read_b128 v[204:207], v150 offset:32768
	ds_read_b128 v[208:211], v150 offset:33792
	ds_read_b128 v[212:215], v150 offset:34816
	ds_read_b128 v[216:219], v150 offset:35840
	ds_read_b128 v[220:223], v150 offset:36864
	ds_read_b128 v[224:227], v150 offset:37888
	ds_read_b128 v[228:231], v150 offset:38912
	ds_read_b128 v[232:235], v150 offset:39936
	global_load_lds_dwordx4 v130, s[24:25]
	s_mov_b32 m0, s16
	s_nop 0
	global_load_lds_dwordx4 v132, s[24:25]
	s_waitcnt vmcnt(8)
	s_waitcnt lgkmcnt(0)
	s_barrier
; #define PG8_STAGE(bufoff, gbase) do { _Pragma("unroll") for (int _i = 0; _i < 2; ++_i) \
;     __builtin_amdgcn_global_load_lds((const unsigned*)((const char*)(gbase) + voff[_i]), (LAS unsigned*)(lds + (bufoff) + ldsw + _i * 8192), 16, 0, 0); } while (0)
; #define PG8_LDA(dst, b, h) do { _Pragma("unroll") for (int m = 0; m < 4; ++m) _Pragma("unroll") for (int k = 0; k < 2; ++k) dst[m][k] = *(const LAS bf16x8*)(lds + PG8_SA(b, h) + aoff + m * 2048 + k * 1024); } while (0)
; #define PG8_WAIT_V(n) asm volatile("s_waitcnt vmcnt(" #n ")" ::: "memory")
; #define PG8_WAIT_L(n) asm volatile("s_waitcnt lgkmcnt(" #n ")" ::: "memory")
; #define PG8_BAR __builtin_amdgcn_s_barrier()
; #define PG8_SCHED __builtin_amdgcn_sched_barrier(0)
; template <int EPI, bool ALIGN_EPI = true, bool SP2 = true>
; DI void gemm8_phase(const GemmArgs& g, char* lds_) {
;     ...
;         PG8_WAIT_V(8); PG8_WAIT_L(0); PG8_BAR; PG8_MMA(0, 0, At, B0); PG8_MMA(0, 1, At, B1); PG8_BAR; PG8_SCHED;
;         PG8_LDA(At, 1, 1); PG8_STAGE(PG8_SB(1, 0), b3); PG8_STAGE(PG8_SB(1, 1), b3 + hstep); PG8_STAGE(PG8_SA(1, 0), a3);
;         PG8_WAIT_V(8); PG8_WAIT_L(0); PG8_BAR; PG8_MMA(1, 0, At, B0); PG8_MMA(1, 1, At, B1); PG8_BAR; PG8_SCHED;
	s_setprio 1
	s_waitcnt lgkmcnt(0)
	v_mfma_f32_16x16x32_bf16 v[126:129], v[138:141], v[204:207], v[126:129]
	v_mfma_f32_16x16x32_bf16 v[122:125], v[154:157], v[204:207], v[122:125]
	v_mfma_f32_16x16x32_bf16 v[118:121], v[138:141], v[212:215], v[118:121]
	v_mfma_f32_16x16x32_bf16 v[114:117], v[154:157], v[212:215], v[114:117]
	v_mfma_f32_16x16x32_bf16 v[110:113], v[138:141], v[220:223], v[110:113]
	v_mfma_f32_16x16x32_bf16 v[106:109], v[154:157], v[220:223], v[106:109]
	v_mfma_f32_16x16x32_bf16 v[102:105], v[138:141], v[228:231], v[102:105]
	v_mfma_f32_16x16x32_bf16 v[98:101], v[154:157], v[228:231], v[98:101]
	v_mfma_f32_16x16x32_bf16 v[126:129], v[142:145], v[208:211], v[126:129]
	v_mfma_f32_16x16x32_bf16 v[122:125], v[158:161], v[208:211], v[122:125]
	v_mfma_f32_16x16x32_bf16 v[118:121], v[142:145], v[216:219], v[118:121]
	v_mfma_f32_16x16x32_bf16 v[114:117], v[158:161], v[216:219], v[114:117]
	v_mfma_f32_16x16x32_bf16 v[110:113], v[142:145], v[224:227], v[110:113]
	v_mfma_f32_16x16x32_bf16 v[106:109], v[158:161], v[224:227], v[106:109]
	v_mfma_f32_16x16x32_bf16 v[102:105], v[142:145], v[232:235], v[102:105]
	v_mfma_f32_16x16x32_bf16 v[98:101], v[158:161], v[232:235], v[98:101]
	s_setprio 0
	s_setprio 1
	v_mfma_f32_16x16x32_bf16 v[94:97], v[168:171], v[204:207], v[94:97]
	v_mfma_f32_16x16x32_bf16 v[90:93], v[196:199], v[204:207], v[90:93]
	v_mfma_f32_16x16x32_bf16 v[86:89], v[168:171], v[212:215], v[86:89]
	v_mfma_f32_16x16x32_bf16 v[82:85], v[196:199], v[212:215], v[82:85]
	v_mfma_f32_16x16x32_bf16 v[78:81], v[168:171], v[220:223], v[78:81]
	v_mfma_f32_16x16x32_bf16 v[74:77], v[196:199], v[220:223], v[74:77]
	v_mfma_f32_16x16x32_bf16 v[70:73], v[168:171], v[228:231], v[70:73]
	v_mfma_f32_16x16x32_bf16 v[66:69], v[196:199], v[228:231], v[66:69]
	v_mfma_f32_16x16x32_bf16 v[94:97], v[192:195], v[208:211], v[94:97]
	v_mfma_f32_16x16x32_bf16 v[90:93], v[200:203], v[208:211], v[90:93]
	v_mfma_f32_16x16x32_bf16 v[86:89], v[192:195], v[216:219], v[86:89]
	v_mfma_f32_16x16x32_bf16 v[82:85], v[200:203], v[216:219], v[82:85]
	v_mfma_f32_16x16x32_bf16 v[78:81], v[192:195], v[224:227], v[78:81]
	v_mfma_f32_16x16x32_bf16 v[74:77], v[200:203], v[224:227], v[74:77]
	v_mfma_f32_16x16x32_bf16 v[70:73], v[192:195], v[232:235], v[70:73]
	v_mfma_f32_16x16x32_bf16 v[66:69], v[200:203], v[232:235], v[66:69]
	s_setprio 0
	s_barrier
	s_mov_b32 m0, s19
	s_add_u32 s24, s86, 0x40080
	ds_read_b128 v[204:207], v150 offset:49152
	ds_read_b128 v[208:211], v150 offset:50176
	ds_read_b128 v[212:215], v150 offset:51200
	ds_read_b128 v[216:219], v150 offset:52224
	ds_read_b128 v[220:223], v150 offset:53248
	ds_read_b128 v[224:227], v150 offset:54272
	ds_read_b128 v[228:231], v150 offset:55296
	ds_read_b128 v[232:235], v150 offset:56320
	global_load_lds_dwordx4 v164, s[86:87]
	s_mov_b32 m0, s28
	s_addc_u32 s25, s87, 0
	global_load_lds_dwordx4 v165, s[86:87]
	s_mov_b32 m0, s69
	s_nop 0
	global_load_lds_dwordx4 v130, s[24:25]
	s_mov_b32 m0, s20
	s_nop 0
	global_load_lds_dwordx4 v132, s[24:25]
	s_mov_b32 m0, s57
	s_nop 0
	global_load_lds_dwordx4 v164, s[90:91]
	s_mov_b32 m0, s68
	s_nop 0
	global_load_lds_dwordx4 v165, s[90:91]
	s_waitcnt vmcnt(8)
	s_waitcnt lgkmcnt(0)
	s_barrier
	s_setprio 1
	s_waitcnt lgkmcnt(0)
	v_mfma_f32_16x16x32_bf16 v[62:65], v[138:141], v[204:207], v[62:65]
	v_mfma_f32_16x16x32_bf16 v[58:61], v[154:157], v[204:207], v[58:61]
	v_mfma_f32_16x16x32_bf16 v[54:57], v[138:141], v[212:215], v[54:57]
	v_mfma_f32_16x16x32_bf16 v[50:53], v[154:157], v[212:215], v[50:53]
	v_mfma_f32_16x16x32_bf16 v[46:49], v[138:141], v[220:223], v[46:49]
	v_mfma_f32_16x16x32_bf16 v[42:45], v[154:157], v[220:223], v[42:45]
	v_mfma_f32_16x16x32_bf16 v[38:41], v[138:141], v[228:231], v[38:41]
	v_mfma_f32_16x16x32_bf16 v[34:37], v[154:157], v[228:231], v[34:37]
	v_mfma_f32_16x16x32_bf16 v[62:65], v[142:145], v[208:211], v[62:65]
	v_mfma_f32_16x16x32_bf16 v[58:61], v[158:161], v[208:211], v[58:61]
	v_mfma_f32_16x16x32_bf16 v[54:57], v[142:145], v[216:219], v[54:57]
	v_mfma_f32_16x16x32_bf16 v[50:53], v[158:161], v[216:219], v[50:53]
	v_mfma_f32_16x16x32_bf16 v[46:49], v[142:145], v[224:227], v[46:49]
	v_mfma_f32_16x16x32_bf16 v[42:45], v[158:161], v[224:227], v[42:45]
	v_mfma_f32_16x16x32_bf16 v[38:41], v[142:145], v[232:235], v[38:41]
	v_mfma_f32_16x16x32_bf16 v[34:37], v[158:161], v[232:235], v[34:37]
	s_setprio 0
	s_setprio 1
	v_mfma_f32_16x16x32_bf16 v[30:33], v[168:171], v[204:207], v[30:33]
	v_mfma_f32_16x16x32_bf16 v[26:29], v[196:199], v[204:207], v[26:29]
	v_mfma_f32_16x16x32_bf16 v[22:25], v[168:171], v[212:215], v[22:25]
	v_mfma_f32_16x16x32_bf16 v[18:21], v[196:199], v[212:215], v[18:21]
	v_mfma_f32_16x16x32_bf16 v[14:17], v[168:171], v[220:223], v[14:17]
	v_mfma_f32_16x16x32_bf16 v[10:13], v[196:199], v[220:223], v[10:13]
	v_mfma_f32_16x16x32_bf16 v[6:9], v[168:171], v[228:231], v[6:9]
	v_mfma_f32_16x16x32_bf16 v[2:5], v[196:199], v[228:231], v[2:5]
	v_mfma_f32_16x16x32_bf16 v[30:33], v[192:195], v[208:211], v[30:33]
	v_mfma_f32_16x16x32_bf16 v[26:29], v[200:203], v[208:211], v[26:29]
	v_mfma_f32_16x16x32_bf16 v[22:25], v[192:195], v[216:219], v[22:25]
	v_mfma_f32_16x16x32_bf16 v[18:21], v[200:203], v[216:219], v[18:21]
	v_mfma_f32_16x16x32_bf16 v[14:17], v[192:195], v[224:227], v[14:17]
	v_mfma_f32_16x16x32_bf16 v[10:13], v[200:203], v[224:227], v[10:13]
	v_mfma_f32_16x16x32_bf16 v[6:9], v[192:195], v[232:235], v[6:9]
	v_mfma_f32_16x16x32_bf16 v[2:5], v[200:203], v[232:235], v[2:5]
	s_setprio 0
	s_barrier
	s_add_i32 vcc_lo, vcc_lo, 2
	s_add_u32 s50, s50, 0x100
	s_addc_u32 s51, s51, 0
	s_cmp_gt_u32 vcc_lo, 13
	s_mov_b64 s[34:35], s[40:41]
	s_cbranch_scc0 .LBB0_381
	s_and_b64 vcc, exec, s[42:43]
	s_cbranch_vccz .LBB0_384
	s_barrier

; #define PG8_STAGE(bufoff, gbase) do { _Pragma("unroll") for (int _i = 0; _i < 2; ++_i) \
;     __builtin_amdgcn_global_load_lds((const unsigned*)((const char*)(gbase) + voff[_i]), (LAS unsigned*)(lds + (bufoff) + ldsw + _i * 8192), 16, 0, 0); } while (0)
; #define PG8_LDA(dst, b, h) do { _Pragma("unroll") for (int m = 0; m < 4; ++m) _Pragma("unroll") for (int k = 0; k < 2; ++k) dst[m][k] = *(const LAS bf16x8*)(lds + PG8_SA(b, h) + aoff + m * 2048 + k * 1024); } while (0)
; #define PG8_LDB(dst, b, h) do { _Pragma("unroll") for (int n = 0; n < 2; ++n) _Pragma("unroll") for (int k = 0; k < 2; ++k) dst[n][k] = *(const LAS bf16x8*)(lds + PG8_SB(b, h) + boff + n * 2048 + k * 1024); } while (0)
; #define PG8_WAIT_V(n) asm volatile("s_waitcnt vmcnt(" #n ")" ::: "memory")
; #define PG8_WAIT_L(n) asm volatile("s_waitcnt lgkmcnt(" #n ")" ::: "memory")
; #define PG8_BAR __builtin_amdgcn_s_barrier()
; #define PG8_SCHED __builtin_amdgcn_sched_barrier(0)
; template <int EPI, bool ALIGN_EPI = true, bool SP2 = true>
; DI void gemm8_phase(const GemmArgs& g, char* lds_) {
;     ...
;     const int nid = (int)blockIdx.x + (ui + 1) * G;
;     const bool has_next = nid < total;
;     if (has_next) tile_map(nid, g.NTm, g.NTn, npm, npn, g.gm);
;     const char* nA = has_next ? (const char*)g.A0 + (size_t)npm * tstep : cA;
;     const char* nB = has_next ? (const char*)g.Bt0 + (size_t)npn * tstep : cB;
; #pragma unroll 1
;     for (int t = 0; t < nt; t += 2) {
;       const bool last = (t == nt - 2);
;       const char* a1 = cA + (size_t)(t + 1) * kstep;
;       const char* a2 = last ? nA : cA + (size_t)(t + 2) * kstep;
;       const char* b2 = last ? nB : cB + (size_t)(t + 2) * kstep;
;       const char* a3 = a2 + kstep; const char* b3 = b2 + kstep;
;       if constexpr (SP2) {
;         const bool relax = EPI_VM > 0 && t == 0 && ui > 0;
;         PG8_LDB(B0, 0, 0); PG8_LDB(B1, 0, 1); PG8_SCHED; PG8_LDA(At, 0, 0); PG8_STAGE(PG8_SA(1, 1), a1 + hstep);
;         if (relax) PG8_WAIT_V(24); else PG8_WAIT_V(8);
;         PG8_WAIT_L(0); PG8_BAR; PG8_MMA(0, 0, At, B0); PG8_MMA(0, 1, At, B1); PG8_BAR; PG8_SCHED;
.LBB0_572:
	s_ashr_i32 s45, s44, 31
	s_lshl_b64 s[24:25], s[44:45], 19
	s_add_u32 s34, s7, s24
	s_addc_u32 s35, s8, s25
	s_and_b64 s[24:25], s[84:85], exec
	s_cselect_b32 s45, s35, s41
	s_cselect_b32 s47, s34, s40
	s_add_u32 s50, s40, 0x100
	v_mov_b32_e32 v2, 0
	s_addc_u32 s51, s41, 0
	s_mov_b32 s69, -2
	v_mov_b32_e32 v3, v2
	v_mov_b32_e32 v4, v2
	v_mov_b32_e32 v5, v2
	v_mov_b32_e32 v6, v2
	v_mov_b32_e32 v7, v2
	v_mov_b32_e32 v8, v2
	v_mov_b32_e32 v9, v2
	v_mov_b32_e32 v10, v2
	v_mov_b32_e32 v11, v2
	v_mov_b32_e32 v12, v2
	v_mov_b32_e32 v13, v2
	v_mov_b32_e32 v14, v2
	v_mov_b32_e32 v15, v2
	v_mov_b32_e32 v16, v2
	v_mov_b32_e32 v17, v2
	v_mov_b32_e32 v18, v2
	v_mov_b32_e32 v19, v2
	v_mov_b32_e32 v20, v2
	v_mov_b32_e32 v21, v2
	v_mov_b32_e32 v22, v2
	v_mov_b32_e32 v23, v2
	v_mov_b32_e32 v24, v2
	v_mov_b32_e32 v25, v2
	v_mov_b32_e32 v26, v2
	v_mov_b32_e32 v27, v2
	v_mov_b32_e32 v28, v2
	v_mov_b32_e32 v29, v2
	v_mov_b32_e32 v30, v2
	v_mov_b32_e32 v31, v2
	v_mov_b32_e32 v32, v2
	v_mov_b32_e32 v33, v2
	v_mov_b32_e32 v34, v2
	v_mov_b32_e32 v35, v2
	v_mov_b32_e32 v36, v2
	v_mov_b32_e32 v37, v2
	v_mov_b32_e32 v46, v2
	v_mov_b32_e32 v47, v2
	v_mov_b32_e32 v48, v2
	v_mov_b32_e32 v49, v2
	v_mov_b32_e32 v38, v2
	v_mov_b32_e32 v39, v2
	v_mov_b32_e32 v40, v2
	v_mov_b32_e32 v41, v2
	v_mov_b32_e32 v54, v2
	v_mov_b32_e32 v55, v2
	v_mov_b32_e32 v56, v2
	v_mov_b32_e32 v57, v2
	v_mov_b32_e32 v42, v2
	v_mov_b32_e32 v43, v2
	v_mov_b32_e32 v44, v2
	v_mov_b32_e32 v45, v2
	v_mov_b32_e32 v58, v2
	v_mov_b32_e32 v59, v2
	v_mov_b32_e32 v60, v2
	v_mov_b32_e32 v61, v2
	v_mov_b32_e32 v50, v2
	v_mov_b32_e32 v51, v2
	v_mov_b32_e32 v52, v2
	v_mov_b32_e32 v53, v2
	v_mov_b32_e32 v62, v2
	v_mov_b32_e32 v63, v2
	v_mov_b32_e32 v64, v2
	v_mov_b32_e32 v65, v2
	v_mov_b32_e32 v66, v2
	v_mov_b32_e32 v67, v2
	v_mov_b32_e32 v68, v2
	v_mov_b32_e32 v69, v2
	v_mov_b32_e32 v70, v2
	v_mov_b32_e32 v71, v2
	v_mov_b32_e32 v72, v2
	v_mov_b32_e32 v73, v2
	v_mov_b32_e32 v74, v2
	v_mov_b32_e32 v75, v2
	v_mov_b32_e32 v76, v2
	v_mov_b32_e32 v77, v2
	v_mov_b32_e32 v78, v2
	v_mov_b32_e32 v79, v2
	v_mov_b32_e32 v80, v2
	v_mov_b32_e32 v81, v2
	v_mov_b32_e32 v82, v2
	v_mov_b32_e32 v83, v2
	v_mov_b32_e32 v84, v2
	v_mov_b32_e32 v85, v2
	v_mov_b32_e32 v86, v2
	v_mov_b32_e32 v87, v2
	v_mov_b32_e32 v88, v2
	v_mov_b32_e32 v89, v2
	v_mov_b32_e32 v90, v2
	v_mov_b32_e32 v91, v2
	v_mov_b32_e32 v92, v2
	v_mov_b32_e32 v93, v2
	v_mov_b32_e32 v94, v2
	v_mov_b32_e32 v95, v2
	v_mov_b32_e32 v96, v2
	v_mov_b32_e32 v97, v2
	v_mov_b32_e32 v98, v2
	v_mov_b32_e32 v99, v2
	v_mov_b32_e32 v100, v2
	v_mov_b32_e32 v101, v2
	v_mov_b32_e32 v110, v2
	v_mov_b32_e32 v111, v2
	v_mov_b32_e32 v112, v2
	v_mov_b32_e32 v113, v2
	v_mov_b32_e32 v102, v2
	v_mov_b32_e32 v103, v2
	v_mov_b32_e32 v104, v2
	v_mov_b32_e32 v105, v2
	v_mov_b32_e32 v118, v2
	v_mov_b32_e32 v119, v2
	v_mov_b32_e32 v120, v2
	v_mov_b32_e32 v121, v2
	v_mov_b32_e32 v106, v2
	v_mov_b32_e32 v107, v2
	v_mov_b32_e32 v108, v2
	v_mov_b32_e32 v109, v2
	v_mov_b32_e32 v122, v2
	v_mov_b32_e32 v123, v2
	v_mov_b32_e32 v124, v2
	v_mov_b32_e32 v125, v2
	v_mov_b32_e32 v114, v2
	v_mov_b32_e32 v115, v2
	v_mov_b32_e32 v116, v2
	v_mov_b32_e32 v117, v2
	v_mov_b32_e32 v126, v2
	v_mov_b32_e32 v127, v2
	v_mov_b32_e32 v128, v2
	v_mov_b32_e32 v129, v2
	v_add_u32_e32 v164, 0x80, v130
	v_add_u32_e32 v165, 0x80, v132
	v_add_u32_e32 v172, 0x10000, v142
.LBB0_573:
	ds_read_b128 v[146:149], v172
	ds_read_b128 v[150:153], v172 offset:1024
	ds_read_b128 v[154:157], v172 offset:2048
	ds_read_b128 v[158:161], v172 offset:3072
	ds_read_b128 v[168:171], v172 offset:16384
	ds_read_b128 v[192:195], v172 offset:17408
	ds_read_b128 v[196:199], v172 offset:18432
	ds_read_b128 v[200:203], v172 offset:19456
	s_add_u32 s40, s38, 0x100
	s_addc_u32 s41, s39, 0
	s_cmp_eq_u32 s69, 12
	s_cselect_b32 s91, s49, s41
	s_cselect_b32 s90, s48, s40
	s_cselect_b32 s87, s45, s51
	s_cselect_b32 s86, s47, s50
	s_add_i32 m0, s9, 0xc000
	ds_read_b128 v[204:207], v141
	ds_read_b128 v[208:211], v141 offset:1024
	ds_read_b128 v[212:215], v141 offset:2048
	ds_read_b128 v[216:219], v141 offset:3072
	ds_read_b128 v[220:223], v141 offset:4096
	ds_read_b128 v[224:227], v141 offset:5120
	ds_read_b128 v[228:231], v141 offset:6144
	ds_read_b128 v[232:235], v141 offset:7168
	global_load_lds_dwordx4 v134, s[38:39]
	s_add_i32 m0, s9, 0xe000
	s_nop 0
	global_load_lds_dwordx4 v136, s[38:39]
	s_waitcnt vmcnt(8)
	s_waitcnt lgkmcnt(0)
	s_barrier
	s_setprio 1
	s_waitcnt lgkmcnt(0)
	v_mfma_f32_16x16x32_bf16 v[126:129], v[146:149], v[204:207], v[126:129]
	v_mfma_f32_16x16x32_bf16 v[114:117], v[154:157], v[204:207], v[114:117]
	v_mfma_f32_16x16x32_bf16 v[122:125], v[146:149], v[212:215], v[122:125]
	v_mfma_f32_16x16x32_bf16 v[106:109], v[154:157], v[212:215], v[106:109]
	v_mfma_f32_16x16x32_bf16 v[118:121], v[146:149], v[220:223], v[118:121]
	v_mfma_f32_16x16x32_bf16 v[102:105], v[154:157], v[220:223], v[102:105]
	v_mfma_f32_16x16x32_bf16 v[110:113], v[146:149], v[228:231], v[110:113]
	v_mfma_f32_16x16x32_bf16 v[98:101], v[154:157], v[228:231], v[98:101]
	v_mfma_f32_16x16x32_bf16 v[126:129], v[150:153], v[208:211], v[126:129]
	v_mfma_f32_16x16x32_bf16 v[114:117], v[158:161], v[208:211], v[114:117]
	v_mfma_f32_16x16x32_bf16 v[122:125], v[150:153], v[216:219], v[122:125]
	v_mfma_f32_16x16x32_bf16 v[106:109], v[158:161], v[216:219], v[106:109]
	v_mfma_f32_16x16x32_bf16 v[118:121], v[150:153], v[224:227], v[118:121]
	v_mfma_f32_16x16x32_bf16 v[102:105], v[158:161], v[224:227], v[102:105]
	v_mfma_f32_16x16x32_bf16 v[110:113], v[150:153], v[232:235], v[110:113]
	v_mfma_f32_16x16x32_bf16 v[98:101], v[158:161], v[232:235], v[98:101]
	s_setprio 0
	s_setprio 1
	v_mfma_f32_16x16x32_bf16 v[94:97], v[168:171], v[204:207], v[94:97]
	v_mfma_f32_16x16x32_bf16 v[90:93], v[196:199], v[204:207], v[90:93]
	v_mfma_f32_16x16x32_bf16 v[86:89], v[168:171], v[212:215], v[86:89]
	v_mfma_f32_16x16x32_bf16 v[82:85], v[196:199], v[212:215], v[82:85]
	v_mfma_f32_16x16x32_bf16 v[78:81], v[168:171], v[220:223], v[78:81]
	v_mfma_f32_16x16x32_bf16 v[74:77], v[196:199], v[220:223], v[74:77]
	v_mfma_f32_16x16x32_bf16 v[70:73], v[168:171], v[228:231], v[70:73]
	v_mfma_f32_16x16x32_bf16 v[66:69], v[196:199], v[228:231], v[66:69]
	v_mfma_f32_16x16x32_bf16 v[94:97], v[192:195], v[208:211], v[94:97]
	v_mfma_f32_16x16x32_bf16 v[90:93], v[200:203], v[208:211], v[90:93]
	v_mfma_f32_16x16x32_bf16 v[86:89], v[192:195], v[216:219], v[86:89]
	v_mfma_f32_16x16x32_bf16 v[82:85], v[200:203], v[216:219], v[82:85]
	v_mfma_f32_16x16x32_bf16 v[78:81], v[192:195], v[224:227], v[78:81]
	v_mfma_f32_16x16x32_bf16 v[74:77], v[200:203], v[224:227], v[74:77]
	v_mfma_f32_16x16x32_bf16 v[70:73], v[192:195], v[232:235], v[70:73]
	v_mfma_f32_16x16x32_bf16 v[66:69], v[200:203], v[232:235], v[66:69]
	s_setprio 0
	s_barrier
; #define PG8_STAGE(bufoff, gbase) do { _Pragma("unroll") for (int _i = 0; _i < 2; ++_i) \
;     __builtin_amdgcn_global_load_lds((const unsigned*)((const char*)(gbase) + voff[_i]), (LAS unsigned*)(lds + (bufoff) + ldsw + _i * 8192), 16, 0, 0); } while (0)
; #define PG8_LDA(dst, b, h) do { _Pragma("unroll") for (int m = 0; m < 4; ++m) _Pragma("unroll") for (int k = 0; k < 2; ++k) dst[m][k] = *(const LAS bf16x8*)(lds + PG8_SA(b, h) + aoff + m * 2048 + k * 1024); } while (0)
; #define PG8_LDB(dst, b, h) do { _Pragma("unroll") for (int n = 0; n < 2; ++n) _Pragma("unroll") for (int k = 0; k < 2; ++k) dst[n][k] = *(const LAS bf16x8*)(lds + PG8_SB(b, h) + boff + n * 2048 + k * 1024); } while (0)
; #define PG8_WAIT_V(n) asm volatile("s_waitcnt vmcnt(" #n ")" ::: "memory")
; #define PG8_WAIT_L(n) asm volatile("s_waitcnt lgkmcnt(" #n ")" ::: "memory")
; #define PG8_BAR __builtin_amdgcn_s_barrier()
; #define PG8_SCHED __builtin_amdgcn_sched_barrier(0)
; template <int EPI, bool ALIGN_EPI = true, bool SP2 = true>
; DI void gemm8_phase(const GemmArgs& g, char* lds_) {
;     ...
;         PG8_LDA(At, 0, 1); PG8_STAGE(PG8_SB(0, 0), b2); PG8_STAGE(PG8_SB(0, 1), b2 + hstep); PG8_STAGE(PG8_SA(0, 0), a2);
;         if (relax) PG8_WAIT_V(24); else PG8_WAIT_V(8);
;         PG8_WAIT_L(0); PG8_BAR; PG8_MMA(1, 0, At, B0); PG8_MMA(1, 1, At, B1); PG8_BAR; PG8_SCHED;
;         PG8_LDB(B0, 1, 0); PG8_LDB(B1, 1, 1); PG8_SCHED; PG8_LDA(At, 1, 0); PG8_STAGE(PG8_SA(0, 1), a2 + hstep);
	s_mov_b32 m0, s10
	s_add_u32 s24, s86, 0x40000
	ds_read_b128 v[204:207], v141 offset:16384
	ds_read_b128 v[208:211], v141 offset:17408
	ds_read_b128 v[212:215], v141 offset:18432
	ds_read_b128 v[216:219], v141 offset:19456
	ds_read_b128 v[220:223], v141 offset:20480
	ds_read_b128 v[224:227], v141 offset:21504
	ds_read_b128 v[228:231], v141 offset:22528
	ds_read_b128 v[232:235], v141 offset:23552
	global_load_lds_dwordx4 v130, s[86:87]
	s_mov_b32 m0, s11
	s_addc_u32 s25, s87, 0
	global_load_lds_dwordx4 v132, s[86:87]
	s_mov_b32 m0, s12
	s_nop 0
	global_load_lds_dwordx4 v130, s[24:25]
	s_mov_b32 m0, s13
	s_nop 0
	global_load_lds_dwordx4 v132, s[24:25]
	s_mov_b32 m0, s9
	s_nop 0
	global_load_lds_dwordx4 v130, s[90:91]
	s_mov_b32 m0, s14
	s_nop 0
	global_load_lds_dwordx4 v132, s[90:91]
	s_waitcnt vmcnt(8)
	s_waitcnt lgkmcnt(0)
	s_barrier
	s_setprio 1
	s_waitcnt lgkmcnt(0)
	v_mfma_f32_16x16x32_bf16 v[62:65], v[146:149], v[204:207], v[62:65]
	v_mfma_f32_16x16x32_bf16 v[50:53], v[154:157], v[204:207], v[50:53]
	v_mfma_f32_16x16x32_bf16 v[58:61], v[146:149], v[212:215], v[58:61]
	v_mfma_f32_16x16x32_bf16 v[42:45], v[154:157], v[212:215], v[42:45]
	v_mfma_f32_16x16x32_bf16 v[54:57], v[146:149], v[220:223], v[54:57]
	v_mfma_f32_16x16x32_bf16 v[38:41], v[154:157], v[220:223], v[38:41]
	v_mfma_f32_16x16x32_bf16 v[46:49], v[146:149], v[228:231], v[46:49]
	v_mfma_f32_16x16x32_bf16 v[34:37], v[154:157], v[228:231], v[34:37]
	v_mfma_f32_16x16x32_bf16 v[62:65], v[150:153], v[208:211], v[62:65]
	v_mfma_f32_16x16x32_bf16 v[50:53], v[158:161], v[208:211], v[50:53]
	v_mfma_f32_16x16x32_bf16 v[58:61], v[150:153], v[216:219], v[58:61]
	v_mfma_f32_16x16x32_bf16 v[42:45], v[158:161], v[216:219], v[42:45]
	v_mfma_f32_16x16x32_bf16 v[54:57], v[150:153], v[224:227], v[54:57]
	v_mfma_f32_16x16x32_bf16 v[38:41], v[158:161], v[224:227], v[38:41]
	v_mfma_f32_16x16x32_bf16 v[46:49], v[150:153], v[232:235], v[46:49]
	v_mfma_f32_16x16x32_bf16 v[34:37], v[158:161], v[232:235], v[34:37]
	s_setprio 0
	s_setprio 1
	v_mfma_f32_16x16x32_bf16 v[30:33], v[168:171], v[204:207], v[30:33]
	v_mfma_f32_16x16x32_bf16 v[26:29], v[196:199], v[204:207], v[26:29]
	v_mfma_f32_16x16x32_bf16 v[22:25], v[168:171], v[212:215], v[22:25]
	v_mfma_f32_16x16x32_bf16 v[18:21], v[196:199], v[212:215], v[18:21]
	v_mfma_f32_16x16x32_bf16 v[14:17], v[168:171], v[220:223], v[14:17]
	v_mfma_f32_16x16x32_bf16 v[10:13], v[196:199], v[220:223], v[10:13]
	v_mfma_f32_16x16x32_bf16 v[6:9], v[168:171], v[228:231], v[6:9]
	v_mfma_f32_16x16x32_bf16 v[2:5], v[196:199], v[228:231], v[2:5]
	v_mfma_f32_16x16x32_bf16 v[30:33], v[192:195], v[208:211], v[30:33]
	v_mfma_f32_16x16x32_bf16 v[26:29], v[200:203], v[208:211], v[26:29]
	v_mfma_f32_16x16x32_bf16 v[22:25], v[192:195], v[216:219], v[22:25]
	v_mfma_f32_16x16x32_bf16 v[18:21], v[200:203], v[216:219], v[18:21]
	v_mfma_f32_16x16x32_bf16 v[14:17], v[192:195], v[224:227], v[14:17]
	v_mfma_f32_16x16x32_bf16 v[10:13], v[200:203], v[224:227], v[10:13]
	v_mfma_f32_16x16x32_bf16 v[6:9], v[192:195], v[232:235], v[6:9]
	v_mfma_f32_16x16x32_bf16 v[2:5], v[200:203], v[232:235], v[2:5]
	s_setprio 0
	s_barrier
	ds_read_b128 v[146:149], v172 offset:32768
	ds_read_b128 v[150:153], v172 offset:33792
	ds_read_b128 v[154:157], v172 offset:34816
	ds_read_b128 v[158:161], v172 offset:35840
	ds_read_b128 v[168:171], v172 offset:49152
	ds_read_b128 v[192:195], v172 offset:50176
	ds_read_b128 v[196:199], v172 offset:51200
	ds_read_b128 v[200:203], v172 offset:52224
	s_add_u32 s24, s90, 0x40000
	s_addc_u32 s25, s91, 0
	s_mov_b32 m0, s15
	ds_read_b128 v[204:207], v141 offset:32768
	ds_read_b128 v[208:211], v141 offset:33792
	ds_read_b128 v[212:215], v141 offset:34816
	ds_read_b128 v[216:219], v141 offset:35840
	ds_read_b128 v[220:223], v141 offset:36864
	ds_read_b128 v[224:227], v141 offset:37888
	ds_read_b128 v[228:231], v141 offset:38912
	ds_read_b128 v[232:235], v141 offset:39936
	global_load_lds_dwordx4 v130, s[24:25]
	s_mov_b32 m0, s16
	s_nop 0
	global_load_lds_dwordx4 v132, s[24:25]
	s_waitcnt vmcnt(8)
	s_waitcnt lgkmcnt(0)
	s_barrier
; #define PG8_STAGE(bufoff, gbase) do { _Pragma("unroll") for (int _i = 0; _i < 2; ++_i) \
;     __builtin_amdgcn_global_load_lds((const unsigned*)((const char*)(gbase) + voff[_i]), (LAS unsigned*)(lds + (bufoff) + ldsw + _i * 8192), 16, 0, 0); } while (0)
; #define PG8_LDA(dst, b, h) do { _Pragma("unroll") for (int m = 0; m < 4; ++m) _Pragma("unroll") for (int k = 0; k < 2; ++k) dst[m][k] = *(const LAS bf16x8*)(lds + PG8_SA(b, h) + aoff + m * 2048 + k * 1024); } while (0)
; #define PG8_WAIT_V(n) asm volatile("s_waitcnt vmcnt(" #n ")" ::: "memory")
; #define PG8_WAIT_L(n) asm volatile("s_waitcnt lgkmcnt(" #n ")" ::: "memory")
; #define PG8_BAR __builtin_amdgcn_s_barrier()
; #define PG8_SCHED __builtin_amdgcn_sched_barrier(0)
; template <int EPI, bool ALIGN_EPI = true, bool SP2 = true>
; DI void gemm8_phase(const GemmArgs& g, char* lds_) {
;     ...
;         PG8_WAIT_V(8); PG8_WAIT_L(0); PG8_BAR; PG8_MMA(0, 0, At, B0); PG8_MMA(0, 1, At, B1); PG8_BAR; PG8_SCHED;
;         PG8_LDA(At, 1, 1); PG8_STAGE(PG8_SB(1, 0), b3); PG8_STAGE(PG8_SB(1, 1), b3 + hstep); PG8_STAGE(PG8_SA(1, 0), a3);
;         PG8_WAIT_V(8); PG8_WAIT_L(0); PG8_BAR; PG8_MMA(1, 0, At, B0); PG8_MMA(1, 1, At, B1); PG8_BAR; PG8_SCHED;
	s_setprio 1
	s_waitcnt lgkmcnt(0)
	v_mfma_f32_16x16x32_bf16 v[126:129], v[146:149], v[204:207], v[126:129]
	v_mfma_f32_16x16x32_bf16 v[114:117], v[154:157], v[204:207], v[114:117]
	v_mfma_f32_16x16x32_bf16 v[122:125], v[146:149], v[212:215], v[122:125]
	v_mfma_f32_16x16x32_bf16 v[106:109], v[154:157], v[212:215], v[106:109]
	v_mfma_f32_16x16x32_bf16 v[118:121], v[146:149], v[220:223], v[118:121]
	v_mfma_f32_16x16x32_bf16 v[102:105], v[154:157], v[220:223], v[102:105]
	v_mfma_f32_16x16x32_bf16 v[110:113], v[146:149], v[228:231], v[110:113]
	v_mfma_f32_16x16x32_bf16 v[98:101], v[154:157], v[228:231], v[98:101]
	v_mfma_f32_16x16x32_bf16 v[126:129], v[150:153], v[208:211], v[126:129]
	v_mfma_f32_16x16x32_bf16 v[114:117], v[158:161], v[208:211], v[114:117]
	v_mfma_f32_16x16x32_bf16 v[122:125], v[150:153], v[216:219], v[122:125]
	v_mfma_f32_16x16x32_bf16 v[106:109], v[158:161], v[216:219], v[106:109]
	v_mfma_f32_16x16x32_bf16 v[118:121], v[150:153], v[224:227], v[118:121]
	v_mfma_f32_16x16x32_bf16 v[102:105], v[158:161], v[224:227], v[102:105]
	v_mfma_f32_16x16x32_bf16 v[110:113], v[150:153], v[232:235], v[110:113]
	v_mfma_f32_16x16x32_bf16 v[98:101], v[158:161], v[232:235], v[98:101]
	s_setprio 0
	s_setprio 1
	v_mfma_f32_16x16x32_bf16 v[94:97], v[168:171], v[204:207], v[94:97]
	v_mfma_f32_16x16x32_bf16 v[90:93], v[196:199], v[204:207], v[90:93]
	v_mfma_f32_16x16x32_bf16 v[86:89], v[168:171], v[212:215], v[86:89]
	v_mfma_f32_16x16x32_bf16 v[82:85], v[196:199], v[212:215], v[82:85]
	v_mfma_f32_16x16x32_bf16 v[78:81], v[168:171], v[220:223], v[78:81]
	v_mfma_f32_16x16x32_bf16 v[74:77], v[196:199], v[220:223], v[74:77]
	v_mfma_f32_16x16x32_bf16 v[70:73], v[168:171], v[228:231], v[70:73]
	v_mfma_f32_16x16x32_bf16 v[66:69], v[196:199], v[228:231], v[66:69]
	v_mfma_f32_16x16x32_bf16 v[94:97], v[192:195], v[208:211], v[94:97]
	v_mfma_f32_16x16x32_bf16 v[90:93], v[200:203], v[208:211], v[90:93]
	v_mfma_f32_16x16x32_bf16 v[86:89], v[192:195], v[216:219], v[86:89]
	v_mfma_f32_16x16x32_bf16 v[82:85], v[200:203], v[216:219], v[82:85]
	v_mfma_f32_16x16x32_bf16 v[78:81], v[192:195], v[224:227], v[78:81]
	v_mfma_f32_16x16x32_bf16 v[74:77], v[200:203], v[224:227], v[74:77]
	v_mfma_f32_16x16x32_bf16 v[70:73], v[192:195], v[232:235], v[70:73]
	v_mfma_f32_16x16x32_bf16 v[66:69], v[200:203], v[232:235], v[66:69]
	s_setprio 0
	s_barrier
	s_mov_b32 m0, s18
	s_add_u32 s24, s86, 0x40080
	ds_read_b128 v[204:207], v141 offset:49152
	ds_read_b128 v[208:211], v141 offset:50176
	ds_read_b128 v[212:215], v141 offset:51200
	ds_read_b128 v[216:219], v141 offset:52224
	ds_read_b128 v[220:223], v141 offset:53248
	ds_read_b128 v[224:227], v141 offset:54272
	ds_read_b128 v[228:231], v141 offset:55296
	ds_read_b128 v[232:235], v141 offset:56320
	global_load_lds_dwordx4 v164, s[86:87]
	s_mov_b32 m0, s19
	s_addc_u32 s25, s87, 0
	global_load_lds_dwordx4 v165, s[86:87]
	s_mov_b32 m0, s28
	s_nop 0
	global_load_lds_dwordx4 v130, s[24:25]
	s_mov_b32 m0, s57
	s_nop 0
	global_load_lds_dwordx4 v132, s[24:25]
	s_mov_b32 m0, s20
	s_nop 0
	global_load_lds_dwordx4 v164, s[90:91]
	s_mov_b32 m0, s21
	s_nop 0
	global_load_lds_dwordx4 v165, s[90:91]
	s_waitcnt vmcnt(8)
	s_waitcnt lgkmcnt(0)
	s_barrier
	s_setprio 1
	s_waitcnt lgkmcnt(0)
	v_mfma_f32_16x16x32_bf16 v[62:65], v[146:149], v[204:207], v[62:65]
	v_mfma_f32_16x16x32_bf16 v[50:53], v[154:157], v[204:207], v[50:53]
	v_mfma_f32_16x16x32_bf16 v[58:61], v[146:149], v[212:215], v[58:61]
	v_mfma_f32_16x16x32_bf16 v[42:45], v[154:157], v[212:215], v[42:45]
	v_mfma_f32_16x16x32_bf16 v[54:57], v[146:149], v[220:223], v[54:57]
	v_mfma_f32_16x16x32_bf16 v[38:41], v[154:157], v[220:223], v[38:41]
	v_mfma_f32_16x16x32_bf16 v[46:49], v[146:149], v[228:231], v[46:49]
	v_mfma_f32_16x16x32_bf16 v[34:37], v[154:157], v[228:231], v[34:37]
	v_mfma_f32_16x16x32_bf16 v[62:65], v[150:153], v[208:211], v[62:65]
	v_mfma_f32_16x16x32_bf16 v[50:53], v[158:161], v[208:211], v[50:53]
	v_mfma_f32_16x16x32_bf16 v[58:61], v[150:153], v[216:219], v[58:61]
	v_mfma_f32_16x16x32_bf16 v[42:45], v[158:161], v[216:219], v[42:45]
	v_mfma_f32_16x16x32_bf16 v[54:57], v[150:153], v[224:227], v[54:57]
	v_mfma_f32_16x16x32_bf16 v[38:41], v[158:161], v[224:227], v[38:41]
	v_mfma_f32_16x16x32_bf16 v[46:49], v[150:153], v[232:235], v[46:49]
	v_mfma_f32_16x16x32_bf16 v[34:37], v[158:161], v[232:235], v[34:37]
	s_setprio 0
	s_setprio 1
	v_mfma_f32_16x16x32_bf16 v[30:33], v[168:171], v[204:207], v[30:33]
	v_mfma_f32_16x16x32_bf16 v[26:29], v[196:199], v[204:207], v[26:29]
	v_mfma_f32_16x16x32_bf16 v[22:25], v[168:171], v[212:215], v[22:25]
	v_mfma_f32_16x16x32_bf16 v[18:21], v[196:199], v[212:215], v[18:21]
	v_mfma_f32_16x16x32_bf16 v[14:17], v[168:171], v[220:223], v[14:17]
	v_mfma_f32_16x16x32_bf16 v[10:13], v[196:199], v[220:223], v[10:13]
	v_mfma_f32_16x16x32_bf16 v[6:9], v[168:171], v[228:231], v[6:9]
	v_mfma_f32_16x16x32_bf16 v[2:5], v[196:199], v[228:231], v[2:5]
	v_mfma_f32_16x16x32_bf16 v[30:33], v[192:195], v[208:211], v[30:33]
	v_mfma_f32_16x16x32_bf16 v[26:29], v[200:203], v[208:211], v[26:29]
	v_mfma_f32_16x16x32_bf16 v[22:25], v[192:195], v[216:219], v[22:25]
	v_mfma_f32_16x16x32_bf16 v[18:21], v[200:203], v[216:219], v[18:21]
	v_mfma_f32_16x16x32_bf16 v[14:17], v[192:195], v[224:227], v[14:17]
	v_mfma_f32_16x16x32_bf16 v[10:13], v[200:203], v[224:227], v[10:13]
	v_mfma_f32_16x16x32_bf16 v[6:9], v[192:195], v[232:235], v[6:9]
	v_mfma_f32_16x16x32_bf16 v[2:5], v[200:203], v[232:235], v[2:5]
	s_setprio 0
	s_barrier
	s_add_i32 s69, s69, 2
	s_add_u32 s50, s50, 0x100
	s_addc_u32 s51, s51, 0
	s_cmp_gt_u32 s69, 13
	s_mov_b64 s[38:39], s[40:41]
	s_cbranch_scc0 .LBB0_573
	s_and_b64 vcc, exec, s[42:43]
	s_cbranch_vccz .LBB0_576
	s_barrier

; #define PG8_STAGE(bufoff, gbase) do { _Pragma("unroll") for (int _i = 0; _i < 2; ++_i) \
;     __builtin_amdgcn_global_load_lds((const unsigned*)((const char*)(gbase) + voff[_i]), (LAS unsigned*)(lds + (bufoff) + ldsw + _i * 8192), 16, 0, 0); } while (0)
; #define PG8_LDA(dst, b, h) do { _Pragma("unroll") for (int m = 0; m < 4; ++m) _Pragma("unroll") for (int k = 0; k < 2; ++k) dst[m][k] = *(const LAS bf16x8*)(lds + PG8_SA(b, h) + aoff + m * 2048 + k * 1024); } while (0)
; #define PG8_LDB(dst, b, h) do { _Pragma("unroll") for (int n = 0; n < 2; ++n) _Pragma("unroll") for (int k = 0; k < 2; ++k) dst[n][k] = *(const LAS bf16x8*)(lds + PG8_SB(b, h) + boff + n * 2048 + k * 1024); } while (0)
; #define PG8_WAIT_V(n) asm volatile("s_waitcnt vmcnt(" #n ")" ::: "memory")
; #define PG8_WAIT_L(n) asm volatile("s_waitcnt lgkmcnt(" #n ")" ::: "memory")
; #define PG8_BAR __builtin_amdgcn_s_barrier()
; #define PG8_SCHED __builtin_amdgcn_sched_barrier(0)
; template <int EPI, bool ALIGN_EPI = true, bool SP2 = true>
; DI void gemm8_phase(const GemmArgs& g, char* lds_) {
;     ...
;     const int nid = (int)blockIdx.x + (ui + 1) * G;
;     const bool has_next = nid < total;
;     if (has_next) tile_map(nid, g.NTm, g.NTn, npm, npn, g.gm);
;     const char* nA = has_next ? (const char*)g.A0 + (size_t)npm * tstep : cA;
;     const char* nB = has_next ? (const char*)g.Bt0 + (size_t)npn * tstep : cB;
; #pragma unroll 1
;     for (int t = 0; t < nt; t += 2) {
;       const bool last = (t == nt - 2);
;       const char* a1 = cA + (size_t)(t + 1) * kstep;
;       const char* a2 = last ? nA : cA + (size_t)(t + 2) * kstep;
;       const char* b2 = last ? nB : cB + (size_t)(t + 2) * kstep;
;       const char* a3 = a2 + kstep; const char* b3 = b2 + kstep;
;       if constexpr (SP2) {
;         const bool relax = EPI_VM > 0 && t == 0 && ui > 0;
;         PG8_LDB(B0, 0, 0); PG8_LDB(B1, 0, 1); PG8_SCHED; PG8_LDA(At, 0, 0); PG8_STAGE(PG8_SA(1, 1), a1 + hstep);
;         if (relax) PG8_WAIT_V(24); else PG8_WAIT_V(8);
;         PG8_WAIT_L(0); PG8_BAR; PG8_MMA(0, 0, At, B0); PG8_MMA(0, 1, At, B1); PG8_BAR; PG8_SCHED;
.LBB0_1054:
	s_add_u32 s48, s48, 0x80
	s_addc_u32 s49, s49, 0
	s_add_u32 vcc_lo, s62, 0x100
	v_mov_b32_e32 v2, 0
	s_addc_u32 vcc_hi, s63, 0
	s_mov_b32 s62, 0
	v_mov_b32_e32 v3, v2
	v_mov_b32_e32 v4, v2
	v_mov_b32_e32 v5, v2
	v_mov_b32_e32 v6, v2
	v_mov_b32_e32 v7, v2
	v_mov_b32_e32 v8, v2
	v_mov_b32_e32 v9, v2
	v_mov_b32_e32 v10, v2
	v_mov_b32_e32 v11, v2
	v_mov_b32_e32 v12, v2
	v_mov_b32_e32 v13, v2
	v_mov_b32_e32 v14, v2
	v_mov_b32_e32 v15, v2
	v_mov_b32_e32 v16, v2
	v_mov_b32_e32 v17, v2
	v_mov_b32_e32 v18, v2
	v_mov_b32_e32 v19, v2
	v_mov_b32_e32 v20, v2
	v_mov_b32_e32 v21, v2
	v_mov_b32_e32 v22, v2
	v_mov_b32_e32 v23, v2
	v_mov_b32_e32 v24, v2
	v_mov_b32_e32 v25, v2
	v_mov_b32_e32 v26, v2
	v_mov_b32_e32 v27, v2
	v_mov_b32_e32 v28, v2
	v_mov_b32_e32 v29, v2
	v_mov_b32_e32 v30, v2
	v_mov_b32_e32 v31, v2
	v_mov_b32_e32 v32, v2
	v_mov_b32_e32 v33, v2
	v_mov_b32_e32 v34, v2
	v_mov_b32_e32 v35, v2
	v_mov_b32_e32 v36, v2
	v_mov_b32_e32 v37, v2
	v_mov_b32_e32 v38, v2
	v_mov_b32_e32 v39, v2
	v_mov_b32_e32 v40, v2
	v_mov_b32_e32 v41, v2
	v_mov_b32_e32 v42, v2
	v_mov_b32_e32 v43, v2
	v_mov_b32_e32 v44, v2
	v_mov_b32_e32 v45, v2
	v_mov_b32_e32 v46, v2
	v_mov_b32_e32 v47, v2
	v_mov_b32_e32 v48, v2
	v_mov_b32_e32 v49, v2
	v_mov_b32_e32 v50, v2
	v_mov_b32_e32 v51, v2
	v_mov_b32_e32 v52, v2
	v_mov_b32_e32 v53, v2
	v_mov_b32_e32 v54, v2
	v_mov_b32_e32 v55, v2
	v_mov_b32_e32 v56, v2
	v_mov_b32_e32 v57, v2
	v_mov_b32_e32 v58, v2
	v_mov_b32_e32 v59, v2
	v_mov_b32_e32 v60, v2
	v_mov_b32_e32 v61, v2
	v_mov_b32_e32 v62, v2
	v_mov_b32_e32 v63, v2
	v_mov_b32_e32 v64, v2
	v_mov_b32_e32 v65, v2
	v_mov_b32_e32 v66, v2
	v_mov_b32_e32 v67, v2
	v_mov_b32_e32 v68, v2
	v_mov_b32_e32 v69, v2
	v_mov_b32_e32 v70, v2
	v_mov_b32_e32 v71, v2
	v_mov_b32_e32 v72, v2
	v_mov_b32_e32 v73, v2
	v_mov_b32_e32 v74, v2
	v_mov_b32_e32 v75, v2
	v_mov_b32_e32 v76, v2
	v_mov_b32_e32 v77, v2
	v_mov_b32_e32 v78, v2
	v_mov_b32_e32 v79, v2
	v_mov_b32_e32 v80, v2
	v_mov_b32_e32 v81, v2
	v_mov_b32_e32 v82, v2
	v_mov_b32_e32 v83, v2
	v_mov_b32_e32 v84, v2
	v_mov_b32_e32 v85, v2
	v_mov_b32_e32 v86, v2
	v_mov_b32_e32 v87, v2
	v_mov_b32_e32 v88, v2
	v_mov_b32_e32 v89, v2
	v_mov_b32_e32 v90, v2
	v_mov_b32_e32 v91, v2
	v_mov_b32_e32 v92, v2
	v_mov_b32_e32 v93, v2
	v_mov_b32_e32 v94, v2
	v_mov_b32_e32 v95, v2
	v_mov_b32_e32 v96, v2
	v_mov_b32_e32 v97, v2
	v_mov_b32_e32 v98, v2
	v_mov_b32_e32 v99, v2
	v_mov_b32_e32 v100, v2
	v_mov_b32_e32 v101, v2
	v_mov_b32_e32 v102, v2
	v_mov_b32_e32 v103, v2
	v_mov_b32_e32 v104, v2
	v_mov_b32_e32 v105, v2
	v_mov_b32_e32 v106, v2
	v_mov_b32_e32 v107, v2
	v_mov_b32_e32 v108, v2
	v_mov_b32_e32 v109, v2
	v_mov_b32_e32 v110, v2
	v_mov_b32_e32 v111, v2
	v_mov_b32_e32 v112, v2
	v_mov_b32_e32 v113, v2
	v_mov_b32_e32 v114, v2
	v_mov_b32_e32 v115, v2
	v_mov_b32_e32 v116, v2
	v_mov_b32_e32 v117, v2
	v_mov_b32_e32 v118, v2
	v_mov_b32_e32 v119, v2
	v_mov_b32_e32 v120, v2
	v_mov_b32_e32 v121, v2
	v_mov_b32_e32 v122, v2
	v_mov_b32_e32 v123, v2
	v_mov_b32_e32 v124, v2
	v_mov_b32_e32 v125, v2
	v_mov_b32_e32 v126, v2
	v_mov_b32_e32 v127, v2
	v_mov_b32_e32 v128, v2
	v_mov_b32_e32 v129, v2
	v_add_u32_e32 v226, 0x80, v0
	v_add_u32_e32 v227, 0x80, v164
	v_add_u32_e32 v228, s28, v0
	v_add_u32_e32 v229, s28, v164
	v_add_u32_e32 v230, s28, v226
	v_add_u32_e32 v231, s28, v227
	v_add_u32_e32 v172, 0x10000, v191
.LBB0_1055:
	s_add_i32 s24, s62, 2
	ds_read_b128 v[130:133], v172
	ds_read_b128 v[134:137], v172 offset:1024
	ds_read_b128 v[138:141], v172 offset:2048
	ds_read_b128 v[142:145], v172 offset:3072
	ds_read_b128 v[146:149], v172 offset:16384
	ds_read_b128 v[150:153], v172 offset:17408
	ds_read_b128 v[154:157], v172 offset:18432
	ds_read_b128 v[158:161], v172 offset:19456
	s_add_u32 s25, s48, 0x80
	s_addc_u32 s26, s49, 0
	s_cmp_eq_u32 s87, s62
	s_cselect_b32 s62, s44, s25
	s_cselect_b32 s63, s45, s26
	s_cselect_b32 s27, s47, vcc_hi
	s_cselect_b32 s26, s46, vcc_lo
	s_add_i32 m0, s13, 0xc000
	ds_read_b128 v[194:197], v192
	ds_read_b128 v[198:201], v192 offset:1024
	ds_read_b128 v[202:205], v192 offset:2048
	ds_read_b128 v[206:209], v192 offset:3072
	ds_read_b128 v[210:213], v192 offset:4096
	ds_read_b128 v[214:217], v192 offset:5120
	ds_read_b128 v[218:221], v192 offset:6144
	ds_read_b128 v[222:225], v192 offset:7168
	global_load_lds_dwordx4 v168, s[48:49]
	s_add_i32 m0, s13, 0xe000
	s_nop 0
	global_load_lds_dwordx4 v170, s[48:49]
	s_waitcnt vmcnt(8)
	s_waitcnt lgkmcnt(0)
	s_barrier
	s_setprio 1
	s_waitcnt lgkmcnt(0)
	v_mfma_f32_16x16x32_bf16 v[126:129], v[130:133], v[194:197], v[126:129]
	v_mfma_f32_16x16x32_bf16 v[122:125], v[138:141], v[194:197], v[122:125]
	v_mfma_f32_16x16x32_bf16 v[118:121], v[130:133], v[202:205], v[118:121]
	v_mfma_f32_16x16x32_bf16 v[114:117], v[138:141], v[202:205], v[114:117]
	v_mfma_f32_16x16x32_bf16 v[110:113], v[130:133], v[210:213], v[110:113]
	v_mfma_f32_16x16x32_bf16 v[106:109], v[138:141], v[210:213], v[106:109]
	v_mfma_f32_16x16x32_bf16 v[102:105], v[130:133], v[218:221], v[102:105]
	v_mfma_f32_16x16x32_bf16 v[98:101], v[138:141], v[218:221], v[98:101]
	v_mfma_f32_16x16x32_bf16 v[126:129], v[134:137], v[198:201], v[126:129]
	v_mfma_f32_16x16x32_bf16 v[122:125], v[142:145], v[198:201], v[122:125]
	v_mfma_f32_16x16x32_bf16 v[118:121], v[134:137], v[206:209], v[118:121]
	v_mfma_f32_16x16x32_bf16 v[114:117], v[142:145], v[206:209], v[114:117]
	v_mfma_f32_16x16x32_bf16 v[110:113], v[134:137], v[214:217], v[110:113]
	v_mfma_f32_16x16x32_bf16 v[106:109], v[142:145], v[214:217], v[106:109]
	v_mfma_f32_16x16x32_bf16 v[102:105], v[134:137], v[222:225], v[102:105]
	v_mfma_f32_16x16x32_bf16 v[98:101], v[142:145], v[222:225], v[98:101]
	s_setprio 0
	s_setprio 1
	v_mfma_f32_16x16x32_bf16 v[94:97], v[146:149], v[194:197], v[94:97]
	v_mfma_f32_16x16x32_bf16 v[90:93], v[154:157], v[194:197], v[90:93]
	v_mfma_f32_16x16x32_bf16 v[86:89], v[146:149], v[202:205], v[86:89]
	v_mfma_f32_16x16x32_bf16 v[82:85], v[154:157], v[202:205], v[82:85]
	v_mfma_f32_16x16x32_bf16 v[78:81], v[146:149], v[210:213], v[78:81]
	v_mfma_f32_16x16x32_bf16 v[74:77], v[154:157], v[210:213], v[74:77]
	v_mfma_f32_16x16x32_bf16 v[70:73], v[146:149], v[218:221], v[70:73]
	v_mfma_f32_16x16x32_bf16 v[66:69], v[154:157], v[218:221], v[66:69]
	v_mfma_f32_16x16x32_bf16 v[94:97], v[150:153], v[198:201], v[94:97]
	v_mfma_f32_16x16x32_bf16 v[90:93], v[158:161], v[198:201], v[90:93]
	v_mfma_f32_16x16x32_bf16 v[86:89], v[150:153], v[206:209], v[86:89]
	v_mfma_f32_16x16x32_bf16 v[82:85], v[158:161], v[206:209], v[82:85]
	v_mfma_f32_16x16x32_bf16 v[78:81], v[150:153], v[214:217], v[78:81]
	v_mfma_f32_16x16x32_bf16 v[74:77], v[158:161], v[214:217], v[74:77]
	v_mfma_f32_16x16x32_bf16 v[70:73], v[150:153], v[222:225], v[70:73]
	v_mfma_f32_16x16x32_bf16 v[66:69], v[158:161], v[222:225], v[66:69]
	s_setprio 0
	s_barrier
; #define PG8_STAGE(bufoff, gbase) do { _Pragma("unroll") for (int _i = 0; _i < 2; ++_i) \
;     __builtin_amdgcn_global_load_lds((const unsigned*)((const char*)(gbase) + voff[_i]), (LAS unsigned*)(lds + (bufoff) + ldsw + _i * 8192), 16, 0, 0); } while (0)
; #define PG8_LDA(dst, b, h) do { _Pragma("unroll") for (int m = 0; m < 4; ++m) _Pragma("unroll") for (int k = 0; k < 2; ++k) dst[m][k] = *(const LAS bf16x8*)(lds + PG8_SA(b, h) + aoff + m * 2048 + k * 1024); } while (0)
; #define PG8_LDB(dst, b, h) do { _Pragma("unroll") for (int n = 0; n < 2; ++n) _Pragma("unroll") for (int k = 0; k < 2; ++k) dst[n][k] = *(const LAS bf16x8*)(lds + PG8_SB(b, h) + boff + n * 2048 + k * 1024); } while (0)
; #define PG8_WAIT_V(n) asm volatile("s_waitcnt vmcnt(" #n ")" ::: "memory")
; #define PG8_WAIT_L(n) asm volatile("s_waitcnt lgkmcnt(" #n ")" ::: "memory")
; #define PG8_BAR __builtin_amdgcn_s_barrier()
; #define PG8_SCHED __builtin_amdgcn_sched_barrier(0)
; template <int EPI, bool ALIGN_EPI = true, bool SP2 = true>
; DI void gemm8_phase(const GemmArgs& g, char* lds_) {
;     ...
;         PG8_LDA(At, 0, 1); PG8_STAGE(PG8_SB(0, 0), b2); PG8_STAGE(PG8_SB(0, 1), b2 + hstep); PG8_STAGE(PG8_SA(0, 0), a2);
;         if (relax) PG8_WAIT_V(24); else PG8_WAIT_V(8);
;         PG8_WAIT_L(0); PG8_BAR; PG8_MMA(1, 0, At, B0); PG8_MMA(1, 1, At, B1); PG8_BAR; PG8_SCHED;
;         PG8_LDB(B0, 1, 0); PG8_LDB(B1, 1, 1); PG8_SCHED; PG8_LDA(At, 1, 0); PG8_STAGE(PG8_SA(0, 1), a2 + hstep);
	s_mov_b32 m0, s14
	ds_read_b128 v[194:197], v192 offset:16384
	ds_read_b128 v[198:201], v192 offset:17408
	ds_read_b128 v[202:205], v192 offset:18432
	ds_read_b128 v[206:209], v192 offset:19456
	ds_read_b128 v[210:213], v192 offset:20480
	ds_read_b128 v[214:217], v192 offset:21504
	ds_read_b128 v[218:221], v192 offset:22528
	ds_read_b128 v[222:225], v192 offset:23552
	global_load_lds_dwordx4 v0, s[26:27]
	s_mov_b32 m0, s15
	s_nop 0
	global_load_lds_dwordx4 v164, s[26:27]
	s_mov_b32 m0, s16
	s_nop 0
	global_load_lds_dwordx4 v228, s[26:27]
	s_mov_b32 m0, s17
	s_nop 0
	global_load_lds_dwordx4 v229, s[26:27]
	s_mov_b32 m0, s13
	s_nop 0
	global_load_lds_dwordx4 v0, s[62:63]
	s_mov_b32 m0, s18
	s_nop 0
	global_load_lds_dwordx4 v164, s[62:63]
	s_waitcnt vmcnt(8)
	s_waitcnt lgkmcnt(0)
	s_barrier
	s_setprio 1
	s_waitcnt lgkmcnt(0)
	v_mfma_f32_16x16x32_bf16 v[62:65], v[130:133], v[194:197], v[62:65]
	v_mfma_f32_16x16x32_bf16 v[58:61], v[138:141], v[194:197], v[58:61]
	v_mfma_f32_16x16x32_bf16 v[54:57], v[130:133], v[202:205], v[54:57]
	v_mfma_f32_16x16x32_bf16 v[50:53], v[138:141], v[202:205], v[50:53]
	v_mfma_f32_16x16x32_bf16 v[46:49], v[130:133], v[210:213], v[46:49]
	v_mfma_f32_16x16x32_bf16 v[42:45], v[138:141], v[210:213], v[42:45]
	v_mfma_f32_16x16x32_bf16 v[38:41], v[130:133], v[218:221], v[38:41]
	v_mfma_f32_16x16x32_bf16 v[34:37], v[138:141], v[218:221], v[34:37]
	v_mfma_f32_16x16x32_bf16 v[62:65], v[134:137], v[198:201], v[62:65]
	v_mfma_f32_16x16x32_bf16 v[58:61], v[142:145], v[198:201], v[58:61]
	v_mfma_f32_16x16x32_bf16 v[54:57], v[134:137], v[206:209], v[54:57]
	v_mfma_f32_16x16x32_bf16 v[50:53], v[142:145], v[206:209], v[50:53]
	v_mfma_f32_16x16x32_bf16 v[46:49], v[134:137], v[214:217], v[46:49]
	v_mfma_f32_16x16x32_bf16 v[42:45], v[142:145], v[214:217], v[42:45]
	v_mfma_f32_16x16x32_bf16 v[38:41], v[134:137], v[222:225], v[38:41]
	v_mfma_f32_16x16x32_bf16 v[34:37], v[142:145], v[222:225], v[34:37]
	s_setprio 0
	s_setprio 1
	v_mfma_f32_16x16x32_bf16 v[30:33], v[146:149], v[194:197], v[30:33]
	v_mfma_f32_16x16x32_bf16 v[26:29], v[154:157], v[194:197], v[26:29]
	v_mfma_f32_16x16x32_bf16 v[22:25], v[146:149], v[202:205], v[22:25]
	v_mfma_f32_16x16x32_bf16 v[18:21], v[154:157], v[202:205], v[18:21]
	v_mfma_f32_16x16x32_bf16 v[14:17], v[146:149], v[210:213], v[14:17]
	v_mfma_f32_16x16x32_bf16 v[10:13], v[154:157], v[210:213], v[10:13]
	v_mfma_f32_16x16x32_bf16 v[6:9], v[146:149], v[218:221], v[6:9]
	v_mfma_f32_16x16x32_bf16 v[2:5], v[154:157], v[218:221], v[2:5]
	v_mfma_f32_16x16x32_bf16 v[30:33], v[150:153], v[198:201], v[30:33]
	v_mfma_f32_16x16x32_bf16 v[26:29], v[158:161], v[198:201], v[26:29]
	v_mfma_f32_16x16x32_bf16 v[22:25], v[150:153], v[206:209], v[22:25]
	v_mfma_f32_16x16x32_bf16 v[18:21], v[158:161], v[206:209], v[18:21]
	v_mfma_f32_16x16x32_bf16 v[14:17], v[150:153], v[214:217], v[14:17]
	v_mfma_f32_16x16x32_bf16 v[10:13], v[158:161], v[214:217], v[10:13]
	v_mfma_f32_16x16x32_bf16 v[6:9], v[150:153], v[222:225], v[6:9]
	v_mfma_f32_16x16x32_bf16 v[2:5], v[158:161], v[222:225], v[2:5]
	s_setprio 0
	s_barrier
	ds_read_b128 v[130:133], v172 offset:32768
	ds_read_b128 v[134:137], v172 offset:33792
	ds_read_b128 v[138:141], v172 offset:34816
	ds_read_b128 v[142:145], v172 offset:35840
	ds_read_b128 v[146:149], v172 offset:49152
	ds_read_b128 v[150:153], v172 offset:50176
	ds_read_b128 v[154:157], v172 offset:51200
	ds_read_b128 v[158:161], v172 offset:52224
	s_mov_b32 m0, s19
	ds_read_b128 v[194:197], v192 offset:32768
	ds_read_b128 v[198:201], v192 offset:33792
	ds_read_b128 v[202:205], v192 offset:34816
	ds_read_b128 v[206:209], v192 offset:35840
	ds_read_b128 v[210:213], v192 offset:36864
	ds_read_b128 v[214:217], v192 offset:37888
	ds_read_b128 v[218:221], v192 offset:38912
	ds_read_b128 v[222:225], v192 offset:39936
	global_load_lds_dwordx4 v228, s[62:63]
	s_mov_b32 m0, s20
	s_nop 0
	global_load_lds_dwordx4 v229, s[62:63]
	s_waitcnt vmcnt(8)
	s_waitcnt lgkmcnt(0)
	s_barrier
	s_setprio 1
	s_waitcnt lgkmcnt(0)
	v_mfma_f32_16x16x32_bf16 v[126:129], v[130:133], v[194:197], v[126:129]
	v_mfma_f32_16x16x32_bf16 v[122:125], v[138:141], v[194:197], v[122:125]
	v_mfma_f32_16x16x32_bf16 v[118:121], v[130:133], v[202:205], v[118:121]
	v_mfma_f32_16x16x32_bf16 v[114:117], v[138:141], v[202:205], v[114:117]
	v_mfma_f32_16x16x32_bf16 v[110:113], v[130:133], v[210:213], v[110:113]
	v_mfma_f32_16x16x32_bf16 v[106:109], v[138:141], v[210:213], v[106:109]
	v_mfma_f32_16x16x32_bf16 v[102:105], v[130:133], v[218:221], v[102:105]
	v_mfma_f32_16x16x32_bf16 v[98:101], v[138:141], v[218:221], v[98:101]
	v_mfma_f32_16x16x32_bf16 v[126:129], v[134:137], v[198:201], v[126:129]
	v_mfma_f32_16x16x32_bf16 v[122:125], v[142:145], v[198:201], v[122:125]
	v_mfma_f32_16x16x32_bf16 v[118:121], v[134:137], v[206:209], v[118:121]
	v_mfma_f32_16x16x32_bf16 v[114:117], v[142:145], v[206:209], v[114:117]
	v_mfma_f32_16x16x32_bf16 v[110:113], v[134:137], v[214:217], v[110:113]
	v_mfma_f32_16x16x32_bf16 v[106:109], v[142:145], v[214:217], v[106:109]
	v_mfma_f32_16x16x32_bf16 v[102:105], v[134:137], v[222:225], v[102:105]
	v_mfma_f32_16x16x32_bf16 v[98:101], v[142:145], v[222:225], v[98:101]
	s_setprio 0
	s_setprio 1
	v_mfma_f32_16x16x32_bf16 v[94:97], v[146:149], v[194:197], v[94:97]
	v_mfma_f32_16x16x32_bf16 v[90:93], v[154:157], v[194:197], v[90:93]
	v_mfma_f32_16x16x32_bf16 v[86:89], v[146:149], v[202:205], v[86:89]
	v_mfma_f32_16x16x32_bf16 v[82:85], v[154:157], v[202:205], v[82:85]
	v_mfma_f32_16x16x32_bf16 v[78:81], v[146:149], v[210:213], v[78:81]
	v_mfma_f32_16x16x32_bf16 v[74:77], v[154:157], v[210:213], v[74:77]
	v_mfma_f32_16x16x32_bf16 v[70:73], v[146:149], v[218:221], v[70:73]
	v_mfma_f32_16x16x32_bf16 v[66:69], v[154:157], v[218:221], v[66:69]
	v_mfma_f32_16x16x32_bf16 v[94:97], v[150:153], v[198:201], v[94:97]
	v_mfma_f32_16x16x32_bf16 v[90:93], v[158:161], v[198:201], v[90:93]
	v_mfma_f32_16x16x32_bf16 v[86:89], v[150:153], v[206:209], v[86:89]
	v_mfma_f32_16x16x32_bf16 v[82:85], v[158:161], v[206:209], v[82:85]
	v_mfma_f32_16x16x32_bf16 v[78:81], v[150:153], v[214:217], v[78:81]
	v_mfma_f32_16x16x32_bf16 v[74:77], v[158:161], v[214:217], v[74:77]
	v_mfma_f32_16x16x32_bf16 v[70:73], v[150:153], v[222:225], v[70:73]
	v_mfma_f32_16x16x32_bf16 v[66:69], v[158:161], v[222:225], v[66:69]
	s_setprio 0
	s_barrier
; #define PG8_STAGE(bufoff, gbase) do { _Pragma("unroll") for (int _i = 0; _i < 2; ++_i) \
;     __builtin_amdgcn_global_load_lds((const unsigned*)((const char*)(gbase) + voff[_i]), (LAS unsigned*)(lds + (bufoff) + ldsw + _i * 8192), 16, 0, 0); } while (0)
; #define PG8_LDA(dst, b, h) do { _Pragma("unroll") for (int m = 0; m < 4; ++m) _Pragma("unroll") for (int k = 0; k < 2; ++k) dst[m][k] = *(const LAS bf16x8*)(lds + PG8_SA(b, h) + aoff + m * 2048 + k * 1024); } while (0)
; #define PG8_WAIT_V(n) asm volatile("s_waitcnt vmcnt(" #n ")" ::: "memory")
; #define PG8_WAIT_L(n) asm volatile("s_waitcnt lgkmcnt(" #n ")" ::: "memory")
; #define PG8_BAR __builtin_amdgcn_s_barrier()
; #define PG8_SCHED __builtin_amdgcn_sched_barrier(0)
; DI void gemm8_resid_epilogue(const GemmArgs& g, f32x4 (&acc)[2][2][4][2], const int brow, const int bcol, const int wr, const int wc, const int fr, const int fq) {
;     ...
;   auto base = [&](int ai, int bj) -> size_t { return (size_t)(brow + ai * 128 + wr * 64 + fr) * DM + bcol + bj * 128 + wc * 32 + fq * 4; };
;   f32x4 ra[4][2], rb[4][2];
;   auto ld = [&](f32x4 (&r)[4][2], size_t ib) {
; #pragma unroll
;     for (int m = 0; m < 4; ++m)
; #pragma unroll
;       for (int n = 0; n < 2; ++n) r[m][n] = *(const f32x4*)(src + ib + (size_t)(m * 16) * DM + n * 16);
;   };
;   auto st = [&](const f32x4 (&r)[4][2], const f32x4 (&a)[4][2], size_t ib) {
; #pragma unroll
;     for (int m = 0; m < 4; ++m)
; #pragma unroll
;       for (int n = 0; n < 2; ++n) {
;         f32x4 o;
;         o.x = r[m][n].x + sc * a[m][n][0]; o.y = r[m][n].y + sc * a[m][n][1];
;         o.z = r[m][n].z + sc * a[m][n][2]; o.w = r[m][n].w + sc * a[m][n][3];
;         *(f32x4*)(X + ib + (size_t)(m * 16) * DM + n * 16) = o;
;       }
;   };
;   const size_t b00 = base(0, 0), b01 = base(0, 1), b10 = base(1, 0), b11 = base(1, 1);
;   ld(ra, b00); ld(rb, b01);
; template <int EPI, bool ALIGN_EPI = true, bool SP2 = true>
; DI void gemm8_phase(const GemmArgs& g, char* lds_) {
;     ...
;         PG8_WAIT_V(8); PG8_WAIT_L(0); PG8_BAR; PG8_MMA(0, 0, At, B0); PG8_MMA(0, 1, At, B1); PG8_BAR; PG8_SCHED;
;         PG8_LDA(At, 1, 1); PG8_STAGE(PG8_SB(1, 0), b3); PG8_STAGE(PG8_SB(1, 1), b3 + hstep); PG8_STAGE(PG8_SA(1, 0), a3);
;         PG8_WAIT_V(8); PG8_WAIT_L(0); PG8_BAR; PG8_MMA(1, 0, At, B0); PG8_MMA(1, 1, At, B1); PG8_BAR; PG8_SCHED;
	s_mov_b32 m0, s51
	ds_read_b128 v[194:197], v192 offset:49152
	ds_read_b128 v[198:201], v192 offset:50176
	ds_read_b128 v[202:205], v192 offset:51200
	ds_read_b128 v[206:209], v192 offset:52224
	ds_read_b128 v[210:213], v192 offset:53248
	ds_read_b128 v[214:217], v192 offset:54272
	ds_read_b128 v[218:221], v192 offset:55296
	ds_read_b128 v[222:225], v192 offset:56320
	global_load_lds_dwordx4 v226, s[26:27]
	s_mov_b32 m0, s57
	s_nop 0
	global_load_lds_dwordx4 v227, s[26:27]
	s_mov_b32 m0, s84
	s_nop 0
	global_load_lds_dwordx4 v230, s[26:27]
	s_mov_b32 m0, s85
	s_nop 0
	global_load_lds_dwordx4 v231, s[26:27]
	s_mov_b32 m0, s68
	s_nop 0
	global_load_lds_dwordx4 v226, s[62:63]
	s_mov_b32 m0, s69
	s_nop 0
	global_load_lds_dwordx4 v227, s[62:63]
	s_waitcnt vmcnt(8)
	s_waitcnt lgkmcnt(0)
	s_barrier
	s_setprio 1
	s_waitcnt lgkmcnt(0)
	v_mfma_f32_16x16x32_bf16 v[62:65], v[130:133], v[194:197], v[62:65]
	v_mfma_f32_16x16x32_bf16 v[58:61], v[138:141], v[194:197], v[58:61]
	v_mfma_f32_16x16x32_bf16 v[54:57], v[130:133], v[202:205], v[54:57]
	v_mfma_f32_16x16x32_bf16 v[50:53], v[138:141], v[202:205], v[50:53]
	v_mfma_f32_16x16x32_bf16 v[46:49], v[130:133], v[210:213], v[46:49]
	v_mfma_f32_16x16x32_bf16 v[42:45], v[138:141], v[210:213], v[42:45]
	v_mfma_f32_16x16x32_bf16 v[38:41], v[130:133], v[218:221], v[38:41]
	v_mfma_f32_16x16x32_bf16 v[34:37], v[138:141], v[218:221], v[34:37]
	v_mfma_f32_16x16x32_bf16 v[62:65], v[134:137], v[198:201], v[62:65]
	v_mfma_f32_16x16x32_bf16 v[58:61], v[142:145], v[198:201], v[58:61]
	v_mfma_f32_16x16x32_bf16 v[54:57], v[134:137], v[206:209], v[54:57]
	v_mfma_f32_16x16x32_bf16 v[50:53], v[142:145], v[206:209], v[50:53]
	v_mfma_f32_16x16x32_bf16 v[46:49], v[134:137], v[214:217], v[46:49]
	v_mfma_f32_16x16x32_bf16 v[42:45], v[142:145], v[214:217], v[42:45]
	v_mfma_f32_16x16x32_bf16 v[38:41], v[134:137], v[222:225], v[38:41]
	v_mfma_f32_16x16x32_bf16 v[34:37], v[142:145], v[222:225], v[34:37]
	s_setprio 0
	s_setprio 1
	v_mfma_f32_16x16x32_bf16 v[30:33], v[146:149], v[194:197], v[30:33]
	v_mfma_f32_16x16x32_bf16 v[26:29], v[154:157], v[194:197], v[26:29]
	v_mfma_f32_16x16x32_bf16 v[22:25], v[146:149], v[202:205], v[22:25]
	v_mfma_f32_16x16x32_bf16 v[18:21], v[154:157], v[202:205], v[18:21]
	v_mfma_f32_16x16x32_bf16 v[14:17], v[146:149], v[210:213], v[14:17]
	v_mfma_f32_16x16x32_bf16 v[10:13], v[154:157], v[210:213], v[10:13]
	v_mfma_f32_16x16x32_bf16 v[6:9], v[146:149], v[218:221], v[6:9]
	v_mfma_f32_16x16x32_bf16 v[2:5], v[154:157], v[218:221], v[2:5]
	v_mfma_f32_16x16x32_bf16 v[30:33], v[150:153], v[198:201], v[30:33]
	v_mfma_f32_16x16x32_bf16 v[26:29], v[158:161], v[198:201], v[26:29]
	v_mfma_f32_16x16x32_bf16 v[22:25], v[150:153], v[206:209], v[22:25]
	v_mfma_f32_16x16x32_bf16 v[18:21], v[158:161], v[206:209], v[18:21]
	v_mfma_f32_16x16x32_bf16 v[14:17], v[150:153], v[214:217], v[14:17]
	v_mfma_f32_16x16x32_bf16 v[10:13], v[158:161], v[214:217], v[10:13]
	v_mfma_f32_16x16x32_bf16 v[6:9], v[150:153], v[222:225], v[6:9]
	v_mfma_f32_16x16x32_bf16 v[2:5], v[158:161], v[222:225], v[2:5]
	s_setprio 0
	s_barrier
	s_add_u32 s48, s48, 0x100
	s_addc_u32 s49, s49, 0
	s_add_u32 vcc_lo, vcc_lo, 0x100
	s_addc_u32 vcc_hi, vcc_hi, 0
	s_cmp_ge_u32 s24, s50
	s_mov_b32 s62, s24
	s_cbranch_scc0 .LBB0_1055
	s_lshl_b32 s23, s23, 8
	s_add_i32 s23, s23, s21
	s_lshl_b32 s24, s91, 8
	v_or_b32_e32 v130, s23, v163
	v_ashrrev_i32_e32 v131, 31, v130
	s_ashr_i32 s25, s24, 31
	v_lshlrev_b64 v[130:131], 10, v[130:131]
	v_mov_b32_e32 v133, s25
	v_or_b32_e32 v132, s24, v166
	v_lshl_add_u64 v[130:131], v[130:131], 0, v[132:133]
	v_add_u32_e32 v134, s23, v193
	v_ashrrev_i32_e32 v135, 31, v134
	v_lshlrev_b64 v[226:227], 2, v[130:131]
	v_lshlrev_b64 v[134:135], 10, v[134:135]
	v_lshl_add_u64 v[130:131], s[40:41], 0, v[226:227]
	v_lshl_add_u64 v[172:173], v[134:135], 0, v[132:133]
	global_load_dwordx4 v[194:197], v[130:131], off
	global_load_dwordx4 v[198:201], v[130:131], off offset:64
	v_add_co_u32_e32 v132, vcc, s89, v130
	s_mov_b32 s23, s86
	s_nop 0
	v_addc_co_u32_e32 v133, vcc, 0, v131, vcc
	global_load_dwordx4 v[202:205], v[132:133], off
	global_load_dwordx4 v[206:209], v[132:133], off offset:64
	v_add_co_u32_e32 v134, vcc, s96, v130
	s_mov_b32 s91, s22
	s_nop 0
	v_addc_co_u32_e32 v135, vcc, 0, v131, vcc
	global_load_dwordx4 v[210:213], v[134:135], off
	global_load_dwordx4 v[214:217], v[134:135], off offset:64
	v_add_co_u32_e32 v228, vcc, s94, v130
	s_mov_b64 s[62:63], s[46:47]
	s_nop 0
	v_addc_co_u32_e32 v229, vcc, 0, v131, vcc
	global_load_dwordx4 v[218:221], v[228:229], off
	global_load_dwordx4 v[222:225], v[228:229], off offset:64
	global_load_dwordx4 v[158:161], v[130:131], off offset:512
	global_load_dwordx4 v[154:157], v[130:131], off offset:576
	global_load_dwordx4 v[150:153], v[132:133], off offset:512
	global_load_dwordx4 v[146:149], v[132:133], off offset:576
	global_load_dwordx4 v[142:145], v[134:135], off offset:512
	global_load_dwordx4 v[138:141], v[134:135], off offset:576
	s_nop 0
	global_load_dwordx4 v[134:137], v[228:229], off offset:512
	global_load_dwordx4 v[130:133], v[228:229], off offset:576
	s_mov_b64 s[48:49], s[44:45]
	s_waitcnt vmcnt(0)
; DI void gemm8_resid_epilogue(const GemmArgs& g, f32x4 (&acc)[2][2][4][2], const int brow, const int bcol, const int wr, const int wc, const int fr, const int fq) {
;     ...
;   auto st = [&](const f32x4 (&r)[4][2], const f32x4 (&a)[4][2], size_t ib) {
; #pragma unroll
;     for (int m = 0; m < 4; ++m)
; #pragma unroll
;       for (int n = 0; n < 2; ++n) {
;         f32x4 o;
;         o.x = r[m][n].x + sc * a[m][n][0]; o.y = r[m][n].y + sc * a[m][n][1];
;         o.z = r[m][n].z + sc * a[m][n][2]; o.w = r[m][n].w + sc * a[m][n][3];
;         *(f32x4*)(X + ib + (size_t)(m * 16) * DM + n * 16) = o;
;       }
;   };
;   const size_t b00 = base(0, 0), b01 = base(0, 1), b10 = base(1, 0), b11 = base(1, 1);
;   ld(ra, b00); ld(rb, b01);
;   st(ra, acc[0][0], b00); ld(ra, b10);
;   st(rb, acc[0][1], b01); ld(rb, b11);
;   st(ra, acc[1][0], b10);
;   st(rb, acc[1][1], b11);
	v_pk_fma_f32 v[194:195], s[0:1], v[126:127], v[194:195]
	v_lshl_add_u64 v[126:127], s[72:73], 0, v[226:227]
	v_pk_fma_f32 v[124:125], s[42:43], v[124:125], v[200:201]
	v_pk_fma_f32 v[122:123], s[0:1], v[122:123], v[198:199]
	global_store_dwordx4 v[126:127], v[122:125], off offset:64
	v_pk_fma_f32 v[196:197], s[42:43], v[128:129], v[196:197]
	global_store_dwordx4 v[126:127], v[194:197], off
	v_pk_fma_f32 v[122:123], s[42:43], v[120:121], v[204:205]
	v_pk_fma_f32 v[120:121], s[0:1], v[118:119], v[202:203]
	v_add_co_u32_e32 v118, vcc, s89, v126
	v_pk_fma_f32 v[116:117], s[42:43], v[116:117], v[208:209]
	s_nop 0
	v_addc_co_u32_e32 v119, vcc, 0, v127, vcc
	v_pk_fma_f32 v[114:115], s[0:1], v[114:115], v[206:207]
	global_store_dwordx4 v[118:119], v[114:117], off offset:64
	v_pk_fma_f32 v[108:109], s[42:43], v[108:109], v[216:217]
	v_pk_fma_f32 v[106:107], s[0:1], v[106:107], v[214:215]
	v_pk_fma_f32 v[114:115], s[42:43], v[112:113], v[212:213]
	v_pk_fma_f32 v[112:113], s[0:1], v[110:111], v[210:211]
	v_add_co_u32_e32 v110, vcc, s96, v126
	v_pk_fma_f32 v[100:101], s[42:43], v[100:101], v[224:225]
	s_nop 0
	v_addc_co_u32_e32 v111, vcc, 0, v127, vcc
	global_store_dwordx4 v[110:111], v[106:109], off offset:64
	v_pk_fma_f32 v[98:99], s[0:1], v[98:99], v[222:223]
	global_store_dwordx4 v[118:119], v[120:123], off
	v_pk_fma_f32 v[106:107], s[42:43], v[104:105], v[220:221]
	v_pk_fma_f32 v[104:105], s[0:1], v[102:103], v[218:219]
	v_add_co_u32_e32 v102, vcc, s94, v126
	v_lshlrev_b64 v[108:109], 2, v[172:173]
	s_nop 0
	v_addc_co_u32_e32 v103, vcc, 0, v127, vcc
	global_store_dwordx4 v[110:111], v[112:115], off
	global_store_dwordx4 v[102:103], v[104:107], off
	global_store_dwordx4 v[102:103], v[98:101], off offset:64
	v_lshl_add_u64 v[116:117], s[40:41], 0, v[108:109]
	global_load_dwordx4 v[104:107], v[116:117], off
	global_load_dwordx4 v[112:115], v[116:117], off offset:64
	v_add_co_u32_e32 v124, vcc, s89, v116
	v_pk_fma_f32 v[96:97], s[42:43], v[96:97], v[160:161]
	s_nop 0
	v_addc_co_u32_e32 v125, vcc, 0, v117, vcc
	global_load_dwordx4 v[120:123], v[124:125], off
	global_load_dwordx4 v[194:197], v[124:125], off offset:64
	v_add_co_u32_e32 v128, vcc, s96, v116
	v_pk_fma_f32 v[94:95], s[0:1], v[94:95], v[158:159]
	s_nop 0
	v_addc_co_u32_e32 v129, vcc, 0, v117, vcc
	global_load_dwordx4 v[198:201], v[128:129], off
	global_load_dwordx4 v[202:205], v[128:129], off offset:64
	v_add_co_u32_e32 v172, vcc, s94, v116
	v_pk_fma_f32 v[92:93], s[42:43], v[92:93], v[156:157]
	s_nop 0
	v_addc_co_u32_e32 v173, vcc, 0, v117, vcc
	v_pk_fma_f32 v[90:91], s[0:1], v[90:91], v[154:155]
	v_pk_fma_f32 v[88:89], s[42:43], v[88:89], v[152:153]
	v_pk_fma_f32 v[86:87], s[0:1], v[86:87], v[150:151]
	v_pk_fma_f32 v[84:85], s[42:43], v[84:85], v[148:149]
	v_pk_fma_f32 v[82:83], s[0:1], v[82:83], v[146:147]
	v_pk_fma_f32 v[80:81], s[42:43], v[80:81], v[144:145]
	v_pk_fma_f32 v[78:79], s[0:1], v[78:79], v[142:143]
	v_pk_fma_f32 v[76:77], s[42:43], v[76:77], v[140:141]
	v_pk_fma_f32 v[74:75], s[0:1], v[74:75], v[138:139]
	v_pk_fma_f32 v[72:73], s[42:43], v[72:73], v[136:137]
	v_pk_fma_f32 v[70:71], s[0:1], v[70:71], v[134:135]
	v_pk_fma_f32 v[68:69], s[42:43], v[68:69], v[132:133]
	v_pk_fma_f32 v[66:67], s[0:1], v[66:67], v[130:131]
	global_load_dwordx4 v[206:209], v[172:173], off
	global_load_dwordx4 v[98:101], v[172:173], off offset:64
	s_waitcnt vmcnt(7)
	v_pk_fma_f32 v[64:65], s[42:43], v[64:65], v[106:107]
	global_store_dwordx4 v[126:127], v[94:97], off offset:512
	global_store_dwordx4 v[126:127], v[90:93], off offset:576
	global_store_dwordx4 v[118:119], v[86:89], off offset:512
	global_store_dwordx4 v[118:119], v[82:85], off offset:576
	global_store_dwordx4 v[110:111], v[78:81], off offset:512
	global_store_dwordx4 v[110:111], v[74:77], off offset:576
	global_store_dwordx4 v[102:103], v[70:73], off offset:512
	global_store_dwordx4 v[102:103], v[66:69], off offset:576
	global_load_dwordx4 v[94:97], v[116:117], off offset:512
	global_load_dwordx4 v[90:93], v[116:117], off offset:576
	global_load_dwordx4 v[86:89], v[124:125], off offset:512
	global_load_dwordx4 v[82:85], v[124:125], off offset:576
	global_load_dwordx4 v[78:81], v[128:129], off offset:512
	global_load_dwordx4 v[74:77], v[128:129], off offset:576
	global_load_dwordx4 v[70:73], v[172:173], off offset:512
	global_load_dwordx4 v[66:69], v[172:173], off offset:576
	v_lshl_add_u64 v[102:103], s[72:73], 0, v[108:109]
	s_waitcnt vmcnt(22)
; DI void gemm8_resid_epilogue(const GemmArgs& g, f32x4 (&acc)[2][2][4][2], const int brow, const int bcol, const int wr, const int wc, const int fr, const int fq) {
;     ...
;   auto st = [&](const f32x4 (&r)[4][2], const f32x4 (&a)[4][2], size_t ib) {
; #pragma unroll
;     for (int m = 0; m < 4; ++m)
; #pragma unroll
;       for (int n = 0; n < 2; ++n) {
;         f32x4 o;
;         o.x = r[m][n].x + sc * a[m][n][0]; o.y = r[m][n].y + sc * a[m][n][1];
;         o.z = r[m][n].z + sc * a[m][n][2]; o.w = r[m][n].w + sc * a[m][n][3];
;         *(f32x4*)(X + ib + (size_t)(m * 16) * DM + n * 16) = o;
;       }
;   };
;   const size_t b00 = base(0, 0), b01 = base(0, 1), b10 = base(1, 0), b11 = base(1, 1);
;   ld(ra, b00); ld(rb, b01);
;   st(ra, acc[0][0], b00); ld(ra, b10);
;   st(rb, acc[0][1], b01); ld(rb, b11);
;   st(ra, acc[1][0], b10);
;   st(rb, acc[1][1], b11);
	v_pk_fma_f32 v[60:61], s[42:43], v[60:61], v[114:115]
	v_pk_fma_f32 v[58:59], s[0:1], v[58:59], v[112:113]
	global_store_dwordx4 v[102:103], v[58:61], off offset:64
	s_waitcnt vmcnt(21)
	v_pk_fma_f32 v[52:53], s[42:43], v[52:53], v[196:197]
	v_pk_fma_f32 v[50:51], s[0:1], v[50:51], v[194:195]
	v_add_co_u32_e32 v58, vcc, s89, v102
	s_waitcnt vmcnt(19)
	v_pk_fma_f32 v[44:45], s[42:43], v[44:45], v[204:205]
	v_addc_co_u32_e32 v59, vcc, 0, v103, vcc
	global_store_dwordx4 v[58:59], v[50:53], off offset:64
	v_pk_fma_f32 v[42:43], s[0:1], v[42:43], v[202:203]
	v_pk_fma_f32 v[62:63], s[0:1], v[62:63], v[104:105]
	v_add_co_u32_e32 v50, vcc, s96, v102
	v_pk_fma_f32 v[56:57], s[42:43], v[56:57], v[122:123]
	s_nop 0
	v_addc_co_u32_e32 v51, vcc, 0, v103, vcc
	global_store_dwordx4 v[50:51], v[42:45], off offset:64
	v_pk_fma_f32 v[54:55], s[0:1], v[54:55], v[120:121]
	v_pk_fma_f32 v[48:49], s[42:43], v[48:49], v[200:201]
	v_add_co_u32_e32 v42, vcc, s94, v102
	v_pk_fma_f32 v[46:47], s[0:1], v[46:47], v[198:199]
	s_nop 0
	v_addc_co_u32_e32 v43, vcc, 0, v103, vcc
	s_waitcnt vmcnt(20)
	v_pk_fma_f32 v[40:41], s[42:43], v[40:41], v[208:209]
	v_pk_fma_f32 v[38:39], s[0:1], v[38:39], v[206:207]
	s_waitcnt vmcnt(19)
	v_pk_fma_f32 v[36:37], s[42:43], v[36:37], v[100:101]
	v_pk_fma_f32 v[34:35], s[0:1], v[34:35], v[98:99]
	s_and_b64 vcc, exec, s[34:35]
	global_store_dwordx4 v[102:103], v[62:65], off
	global_store_dwordx4 v[58:59], v[54:57], off
	global_store_dwordx4 v[50:51], v[46:49], off
	global_store_dwordx4 v[42:43], v[38:41], off
	global_store_dwordx4 v[42:43], v[34:37], off offset:64
	s_waitcnt vmcnt(15)
	v_pk_fma_f32 v[32:33], s[42:43], v[32:33], v[96:97]
	v_pk_fma_f32 v[30:31], s[0:1], v[30:31], v[94:95]
	s_waitcnt vmcnt(14)
	v_pk_fma_f32 v[28:29], s[42:43], v[28:29], v[92:93]
	v_pk_fma_f32 v[26:27], s[0:1], v[26:27], v[90:91]
	s_waitcnt vmcnt(13)
	v_pk_fma_f32 v[24:25], s[42:43], v[24:25], v[88:89]
	v_pk_fma_f32 v[22:23], s[0:1], v[22:23], v[86:87]
	s_waitcnt vmcnt(12)
	v_pk_fma_f32 v[20:21], s[42:43], v[20:21], v[84:85]
	v_pk_fma_f32 v[18:19], s[0:1], v[18:19], v[82:83]
	s_waitcnt vmcnt(11)
	v_pk_fma_f32 v[16:17], s[42:43], v[16:17], v[80:81]
	v_pk_fma_f32 v[14:15], s[0:1], v[14:15], v[78:79]
	s_waitcnt vmcnt(10)
	v_pk_fma_f32 v[12:13], s[42:43], v[12:13], v[76:77]
	v_pk_fma_f32 v[10:11], s[0:1], v[10:11], v[74:75]
	s_waitcnt vmcnt(9)
	v_pk_fma_f32 v[8:9], s[42:43], v[8:9], v[72:73]
	v_pk_fma_f32 v[6:7], s[0:1], v[6:7], v[70:71]
	s_waitcnt vmcnt(8)
	v_pk_fma_f32 v[4:5], s[42:43], v[4:5], v[68:69]
	v_pk_fma_f32 v[2:3], s[0:1], v[2:3], v[66:67]
	global_store_dwordx4 v[102:103], v[30:33], off offset:512
	global_store_dwordx4 v[102:103], v[26:29], off offset:576
	global_store_dwordx4 v[58:59], v[22:25], off offset:512
	global_store_dwordx4 v[58:59], v[18:21], off offset:576
	global_store_dwordx4 v[50:51], v[14:17], off offset:512
	global_store_dwordx4 v[50:51], v[10:13], off offset:576
	global_store_dwordx4 v[42:43], v[6:9], off offset:512
	global_store_dwordx4 v[42:43], v[2:5], off offset:576
	s_cbranch_vccz .LBB0_1050
	s_waitcnt vmcnt(0)
	v_readlane_b32 s64, v254, 53
	v_readlane_b32 s66, v254, 55
	v_readlane_b32 s70, v254, 59
	v_readlane_b32 s24, v254, 51
	s_cmpk_gt_u32 s5, 0xff
	v_readlane_b32 s65, v254, 54
	v_readlane_b32 s67, v254, 56
	s_mov_b32 s55, s59
	v_readlane_b32 s71, v254, 60
	v_readlane_b32 s56, v254, 61
	v_readlane_b32 s79, v254, 62
	v_readlane_b32 s20, v254, 49
	v_readlane_b32 s21, v254, 50
	v_readlane_b32 s25, v254, 52
	s_cbranch_scc1 .LBB0_1059
	s_barrier
